# rstd: folded the 2^-24 fixed-point scale into the fmamk constant (exactly equal f32 result), one VALU less per rstd
# speedup vs baseline: 1.0061x; 1.0061x over previous
.LBB0_79:
	v_lshl_add_u64 v[18:19], s[78:79], 0, v[32:33]
	s_mov_b64 s[0:1], 0x100000
	v_lshl_add_u64 v[20:21], v[18:19], 0, s[0:1]
	v_add_co_u32_e32 v18, vcc, 0x100000, v18
	v_lshl_add_u64 v[34:35], s[78:79], 0, v[30:31]
	s_nop 0
	v_addc_co_u32_e32 v19, vcc, 0, v19, vcc
	global_load_dwordx4 v[22:25], v[18:19], off
	s_nop 0
	global_load_dwordx4 v[18:21], v[20:21], off offset:16
	v_add_co_u32_e32 v36, vcc, s17, v34
	s_mov_b32 s0, 0x4d01000
	s_nop 0
	v_addc_co_u32_e32 v37, vcc, 0, v35, vcc
	v_add_co_u32_e32 v34, vcc, s0, v34
	s_movk_i32 s0, 0xd000
	s_nop 0
	v_addc_co_u32_e32 v35, vcc, 0, v35, vcc
	global_load_dwordx2 v[58:59], v[34:35], off offset:-4096
	global_load_dwordx2 v[62:63], v[36:37], off offset:512
	global_load_dwordx2 v[64:65], v[36:37], off offset:1024
	global_load_dwordx2 v[66:67], v[36:37], off offset:1536
	global_load_dwordx2 v[56:57], v[36:37], off offset:2048
	global_load_dwordx2 v[54:55], v[36:37], off offset:2560
	global_load_dwordx2 v[52:53], v[36:37], off offset:3072
	global_load_dwordx2 v[50:51], v[36:37], off offset:3584
	global_load_dwordx2 v[48:49], v[34:35], off
	global_load_dwordx2 v[46:47], v[34:35], off offset:512
	global_load_dwordx2 v[44:45], v[34:35], off offset:1024
	global_load_dwordx2 v[42:43], v[34:35], off offset:1536
	global_load_dwordx2 v[40:41], v[34:35], off offset:2048
	global_load_dwordx2 v[38:39], v[34:35], off offset:2560
	global_load_dwordx2 v[36:37], v[34:35], off offset:3072
	s_nop 0
	global_load_dwordx2 v[34:35], v[34:35], off offset:3584
	v_add_u32_e32 v26, s30, v26
	v_lshl_add_u64 v[30:31], v[30:31], 0, s[36:37]
	v_lshl_add_u64 v[32:33], v[32:33], 0, s[38:39]
	s_waitcnt vmcnt(17)
	v_ffbh_u32_e32 v0, v23
	v_min_u32_e32 v0, 32, v0
	v_lshlrev_b64 v[22:23], v0, v[22:23]
	v_min_u32_e32 v22, 1, v22
	v_or_b32_e32 v22, v23, v22
	v_cvt_f32_u32_e32 v22, v22
	v_sub_u32_e32 v0, 32, v0
	s_waitcnt vmcnt(15)
	v_and_b32_e32 v23, 0xffff0000, v58
	v_ldexp_f32 v0, v22, v0
	v_fmamk_f32 v0, v0, 0x2e800000, v210
	v_cmp_gt_f32_e32 vcc, s8, v0
	v_mul_f32_e32 v22, 0x4b800000, v0
	s_nop 0
	v_cndmask_b32_e32 v0, v0, v22, vcc
	v_rsq_f32_e32 v0, v0
	s_nop 0
	v_mul_f32_e32 v22, 0x45800000, v0
	v_cndmask_b32_e32 v0, v0, v22, vcc
	v_lshlrev_b32_e32 v22, 16, v58
	v_lshlrev_b32_e32 v58, 16, v59
	v_and_b32_e32 v59, 0xffff0000, v59
	v_pk_mul_f32 v[22:23], v[0:1], v[22:23] op_sel_hi:[0,1]
	v_pk_mul_f32 v[58:59], v[0:1], v[58:59] op_sel_hi:[0,1]
	v_pk_mul_f32 v[60:61], v[4:5], v[58:59]
	v_pk_mul_f32 v[58:59], v[2:3], v[22:23]
	v_add_co_u32_e32 v22, vcc, s0, v28
	s_movk_i32 s0, 0xe000
	s_nop 0
	v_addc_co_u32_e32 v23, vcc, -1, v29, vcc
	global_store_dwordx4 v[22:23], v[58:61], off offset:-3072
	s_waitcnt vmcnt(15)
	s_nop 0
	v_lshlrev_b32_e32 v58, 16, v62
	v_and_b32_e32 v59, 0xffff0000, v62
	v_lshlrev_b32_e32 v60, 16, v63
	v_and_b32_e32 v61, 0xffff0000, v63
	v_pk_mul_f32 v[58:59], v[0:1], v[58:59] op_sel_hi:[0,1]
	v_pk_mul_f32 v[60:61], v[0:1], v[60:61] op_sel_hi:[0,1]
	v_pk_mul_f32 v[60:61], v[8:9], v[60:61]
	v_pk_mul_f32 v[58:59], v[6:7], v[58:59]
	global_store_dwordx4 v[22:23], v[58:61], off offset:-2048
	v_add_co_u32_e32 v62, vcc, s0, v28
	s_waitcnt vmcnt(15)
	v_lshlrev_b32_e32 v58, 16, v64
	v_and_b32_e32 v59, 0xffff0000, v64
	v_lshlrev_b32_e32 v60, 16, v65
	v_and_b32_e32 v61, 0xffff0000, v65
	v_pk_mul_f32 v[58:59], v[0:1], v[58:59] op_sel_hi:[0,1]
	v_pk_mul_f32 v[60:61], v[0:1], v[60:61] op_sel_hi:[0,1]
	v_pk_mul_f32 v[60:61], v[12:13], v[60:61]
	v_pk_mul_f32 v[58:59], v[10:11], v[58:59]
	global_store_dwordx4 v[22:23], v[58:61], off offset:-1024
	s_waitcnt vmcnt(15)
	v_lshlrev_b32_e32 v22, 16, v66
	v_and_b32_e32 v23, 0xffff0000, v66
	v_lshlrev_b32_e32 v58, 16, v67
	v_and_b32_e32 v59, 0xffff0000, v67
	v_pk_mul_f32 v[22:23], v[0:1], v[22:23] op_sel_hi:[0,1]
	v_pk_mul_f32 v[58:59], v[0:1], v[58:59] op_sel_hi:[0,1]
	v_ffbh_u32_e32 v0, v25
	v_min_u32_e32 v0, 32, v0
	v_pk_mul_f32 v[60:61], v[16:17], v[58:59]
	v_pk_mul_f32 v[58:59], v[14:15], v[22:23]
	v_lshlrev_b64 v[22:23], v0, v[24:25]
	v_min_u32_e32 v22, 1, v22
	v_or_b32_e32 v22, v23, v22
	v_cvt_f32_u32_e32 v22, v22
	v_sub_u32_e32 v0, 32, v0
	v_addc_co_u32_e32 v63, vcc, -1, v29, vcc
	v_ldexp_f32 v0, v22, v0
	v_fmamk_f32 v0, v0, 0x2e800000, v210
	v_cmp_gt_f32_e32 vcc, s8, v0
	v_mul_f32_e32 v22, 0x4b800000, v0
	s_waitcnt vmcnt(14)
	v_and_b32_e32 v23, 0xffff0000, v56
	v_cndmask_b32_e32 v0, v0, v22, vcc
	v_rsq_f32_e32 v0, v0
	v_lshlrev_b32_e32 v24, 16, v57
	v_and_b32_e32 v25, 0xffff0000, v57
	s_movk_i32 s0, 0xf000
	v_mul_f32_e32 v22, 0x45800000, v0
	v_cndmask_b32_e32 v0, v0, v22, vcc
	v_lshlrev_b32_e32 v22, 16, v56
	v_pk_mul_f32 v[22:23], v[0:1], v[22:23] op_sel_hi:[0,1]
	v_pk_mul_f32 v[24:25], v[0:1], v[24:25] op_sel_hi:[0,1]
	v_pk_mul_f32 v[24:25], v[4:5], v[24:25]
	v_pk_mul_f32 v[22:23], v[2:3], v[22:23]
	global_store_dwordx4 v[62:63], v[22:25], off offset:-3072
	global_store_dwordx4 v[62:63], v[58:61], off offset:-4096
	s_waitcnt vmcnt(15)
	v_lshlrev_b32_e32 v22, 16, v54
	v_and_b32_e32 v23, 0xffff0000, v54
	v_lshlrev_b32_e32 v24, 16, v55
	v_and_b32_e32 v25, 0xffff0000, v55
	v_pk_mul_f32 v[22:23], v[0:1], v[22:23] op_sel_hi:[0,1]
	v_pk_mul_f32 v[24:25], v[0:1], v[24:25] op_sel_hi:[0,1]
	v_pk_mul_f32 v[24:25], v[8:9], v[24:25]
	v_pk_mul_f32 v[22:23], v[6:7], v[22:23]
	global_store_dwordx4 v[62:63], v[22:25], off offset:-2048
	s_waitcnt vmcnt(15)
	s_nop 0
	v_lshlrev_b32_e32 v22, 16, v52
	v_and_b32_e32 v23, 0xffff0000, v52
	v_lshlrev_b32_e32 v24, 16, v53
	v_and_b32_e32 v25, 0xffff0000, v53
	v_pk_mul_f32 v[22:23], v[0:1], v[22:23] op_sel_hi:[0,1]
	v_pk_mul_f32 v[24:25], v[0:1], v[24:25] op_sel_hi:[0,1]
	v_pk_mul_f32 v[24:25], v[12:13], v[24:25]
	v_pk_mul_f32 v[22:23], v[10:11], v[22:23]
	global_store_dwordx4 v[62:63], v[22:25], off offset:-1024
	s_waitcnt vmcnt(15)
	s_nop 0
	v_lshlrev_b32_e32 v22, 16, v50
	v_and_b32_e32 v23, 0xffff0000, v50
	v_lshlrev_b32_e32 v24, 16, v51
	v_and_b32_e32 v25, 0xffff0000, v51
	v_pk_mul_f32 v[22:23], v[0:1], v[22:23] op_sel_hi:[0,1]
	v_pk_mul_f32 v[24:25], v[0:1], v[24:25] op_sel_hi:[0,1]
	v_ffbh_u32_e32 v0, v19
	v_min_u32_e32 v0, 32, v0
	v_lshlrev_b64 v[18:19], v0, v[18:19]
	v_min_u32_e32 v18, 1, v18
	v_or_b32_e32 v18, v19, v18
	v_cvt_f32_u32_e32 v18, v18
	v_sub_u32_e32 v0, 32, v0
	v_pk_mul_f32 v[24:25], v[16:17], v[24:25]
	v_pk_mul_f32 v[22:23], v[14:15], v[22:23]
	v_ldexp_f32 v0, v18, v0
	v_fmamk_f32 v0, v0, 0x2e800000, v210
	v_cmp_gt_f32_e32 vcc, s8, v0
	v_mul_f32_e32 v18, 0x4b800000, v0
	global_store_dwordx4 v[62:63], v[22:25], off
	v_cndmask_b32_e32 v0, v0, v18, vcc
	v_rsq_f32_e32 v0, v0
	s_waitcnt vmcnt(15)
	v_and_b32_e32 v19, 0xffff0000, v48
	v_lshlrev_b32_e32 v22, 16, v49
	v_and_b32_e32 v23, 0xffff0000, v49
	v_mul_f32_e32 v18, 0x45800000, v0
	v_cndmask_b32_e32 v0, v0, v18, vcc
	v_lshlrev_b32_e32 v18, 16, v48
	v_pk_mul_f32 v[18:19], v[0:1], v[18:19] op_sel_hi:[0,1]
	v_pk_mul_f32 v[22:23], v[0:1], v[22:23] op_sel_hi:[0,1]
	v_pk_mul_f32 v[24:25], v[4:5], v[22:23]
	v_pk_mul_f32 v[22:23], v[2:3], v[18:19]
	v_add_co_u32_e32 v18, vcc, s0, v28
	s_movk_i32 s0, 0x7fff
	s_nop 0
	v_addc_co_u32_e32 v19, vcc, -1, v29, vcc
	global_store_dwordx4 v[18:19], v[22:25], off offset:-3072
	s_waitcnt vmcnt(15)
	s_nop 0
	v_lshlrev_b32_e32 v22, 16, v46
	v_and_b32_e32 v23, 0xffff0000, v46
	v_lshlrev_b32_e32 v24, 16, v47
	v_and_b32_e32 v25, 0xffff0000, v47
	v_pk_mul_f32 v[22:23], v[0:1], v[22:23] op_sel_hi:[0,1]
	v_pk_mul_f32 v[24:25], v[0:1], v[24:25] op_sel_hi:[0,1]
	v_pk_mul_f32 v[24:25], v[8:9], v[24:25]
	v_pk_mul_f32 v[22:23], v[6:7], v[22:23]
	global_store_dwordx4 v[18:19], v[22:25], off offset:-2048
	s_waitcnt vmcnt(15)
	s_nop 0
	v_lshlrev_b32_e32 v22, 16, v44
	v_and_b32_e32 v23, 0xffff0000, v44
	v_lshlrev_b32_e32 v24, 16, v45
	v_and_b32_e32 v25, 0xffff0000, v45
	v_pk_mul_f32 v[22:23], v[0:1], v[22:23] op_sel_hi:[0,1]
	v_pk_mul_f32 v[24:25], v[0:1], v[24:25] op_sel_hi:[0,1]
	v_pk_mul_f32 v[24:25], v[12:13], v[24:25]
	v_pk_mul_f32 v[22:23], v[10:11], v[22:23]
	global_store_dwordx4 v[18:19], v[22:25], off offset:-1024
	s_waitcnt vmcnt(15)
	v_lshlrev_b32_e32 v18, 16, v42
	v_and_b32_e32 v19, 0xffff0000, v42
	v_lshlrev_b32_e32 v22, 16, v43
	v_and_b32_e32 v23, 0xffff0000, v43
	v_pk_mul_f32 v[18:19], v[0:1], v[18:19] op_sel_hi:[0,1]
	v_pk_mul_f32 v[22:23], v[0:1], v[22:23] op_sel_hi:[0,1]
	v_ffbh_u32_e32 v0, v21
	v_min_u32_e32 v0, 32, v0
	v_pk_mul_f32 v[24:25], v[16:17], v[22:23]
	v_pk_mul_f32 v[22:23], v[14:15], v[18:19]
	v_lshlrev_b64 v[18:19], v0, v[20:21]
	v_min_u32_e32 v18, 1, v18
	v_or_b32_e32 v18, v19, v18
	v_cvt_f32_u32_e32 v18, v18
	v_sub_u32_e32 v0, 32, v0
	s_waitcnt vmcnt(14)
	v_and_b32_e32 v19, 0xffff0000, v40
	v_lshlrev_b32_e32 v20, 16, v41
	v_ldexp_f32 v0, v18, v0
	v_fmamk_f32 v0, v0, 0x2e800000, v210
	v_cmp_gt_f32_e32 vcc, s8, v0
	v_mul_f32_e32 v18, 0x4b800000, v0
	v_and_b32_e32 v21, 0xffff0000, v41
	v_cndmask_b32_e32 v0, v0, v18, vcc
	v_rsq_f32_e32 v0, v0
	global_store_dwordx4 v[28:29], v[22:25], off offset:-4096
	v_mul_f32_e32 v18, 0x45800000, v0
	v_cndmask_b32_e32 v0, v0, v18, vcc
	v_lshlrev_b32_e32 v18, 16, v40
	v_pk_mul_f32 v[18:19], v[0:1], v[18:19] op_sel_hi:[0,1]
	v_pk_mul_f32 v[20:21], v[0:1], v[20:21] op_sel_hi:[0,1]
	v_pk_mul_f32 v[20:21], v[4:5], v[20:21]
	v_pk_mul_f32 v[18:19], v[2:3], v[18:19]
	global_store_dwordx4 v[28:29], v[18:21], off offset:-3072
	v_cmp_lt_i32_e32 vcc, s0, v26
	s_or_b64 s[40:41], vcc, s[40:41]
	s_waitcnt vmcnt(15)
	v_lshlrev_b32_e32 v18, 16, v38
	v_and_b32_e32 v19, 0xffff0000, v38
	v_lshlrev_b32_e32 v20, 16, v39
	v_and_b32_e32 v21, 0xffff0000, v39
	v_pk_mul_f32 v[18:19], v[0:1], v[18:19] op_sel_hi:[0,1]
	v_pk_mul_f32 v[20:21], v[0:1], v[20:21] op_sel_hi:[0,1]
	v_pk_mul_f32 v[20:21], v[8:9], v[20:21]
	v_pk_mul_f32 v[18:19], v[6:7], v[18:19]
	global_store_dwordx4 v[28:29], v[18:21], off offset:-2048
	s_waitcnt vmcnt(15)
	s_nop 0
	v_lshlrev_b32_e32 v18, 16, v36
	v_and_b32_e32 v19, 0xffff0000, v36
	v_lshlrev_b32_e32 v20, 16, v37
	v_and_b32_e32 v21, 0xffff0000, v37
	v_pk_mul_f32 v[18:19], v[0:1], v[18:19] op_sel_hi:[0,1]
	v_pk_mul_f32 v[20:21], v[0:1], v[20:21] op_sel_hi:[0,1]
	v_pk_mul_f32 v[20:21], v[12:13], v[20:21]
	v_pk_mul_f32 v[18:19], v[10:11], v[18:19]
	global_store_dwordx4 v[28:29], v[18:21], off offset:-1024
	s_waitcnt vmcnt(15)
	s_nop 0
	v_lshlrev_b32_e32 v18, 16, v34
	v_and_b32_e32 v19, 0xffff0000, v34
	v_lshlrev_b32_e32 v20, 16, v35
	v_and_b32_e32 v21, 0xffff0000, v35
	v_pk_mul_f32 v[18:19], v[0:1], v[18:19] op_sel_hi:[0,1]
	v_pk_mul_f32 v[20:21], v[0:1], v[20:21] op_sel_hi:[0,1]
	v_pk_mul_f32 v[20:21], v[16:17], v[20:21]
	v_pk_mul_f32 v[18:19], v[14:15], v[18:19]
	global_store_dwordx4 v[28:29], v[18:21], off
	v_lshl_add_u64 v[28:29], v[28:29], 0, s[4:5]
	s_andn2_b64 exec, exec, s[40:41]
	s_cbranch_execnz .LBB0_79

.LBB0_109:
	v_mov_b32_e32 v226, v224
	s_lshl_b32 s4, s76, 8
	s_add_i32 s4, s4, s20
	s_mov_b32 s35, 0x800000
	v_and_b32_e32 v183, 15, v226
	v_or_b32_e32 v150, s4, v183
	v_ashrrev_i32_e32 v151, 31, v150
	v_lshl_add_u64 v[136:137], v[150:151], 3, s[38:39]
	global_load_dwordx2 v[152:153], v[136:137], off
	global_load_dwordx2 v[134:135], v[136:137], off offset:128
	global_load_dwordx2 v[132:133], v[136:137], off offset:256
	s_nop 0
	global_load_dwordx2 v[136:137], v[136:137], off offset:384
	v_ashrrev_i32_e32 v0, 1, v226
	v_and_b32_e32 v0, -8, v0
	v_add_u32_e32 v130, s21, v0
	s_lshl_b32 s6, s76, 2
	s_add_i32 s6, s6, s11
	s_lshl_b32 s0, s78, 8
	s_ashr_i32 s1, s0, 31
	s_mul_i32 s7, s6, 0xb000
	s_mul_hi_i32 s5, s6, 0xb000
	s_add_u32 s7, s18, s7
	s_addc_u32 s5, s19, s5
	s_lshl_b64 s[80:81], s[0:1], 1
	s_add_u32 s76, s7, s80
	s_addc_u32 s77, s5, s81
	s_waitcnt vmcnt(0)
	v_ffbh_u32_e32 v0, v153
	v_min_u32_e32 v0, 32, v0
	v_lshlrev_b64 v[152:153], v0, v[152:153]
	v_min_u32_e32 v131, 1, v152
	v_or_b32_e32 v131, v153, v131
	v_cvt_f32_u32_e32 v131, v131
	v_sub_u32_e32 v0, 32, v0
	v_ldexp_f32 v0, v131, v0
	v_fmamk_f32 v0, v0, 0x2e800000, v210
	s_nop 0
	v_rsq_f32_e32 v0, v0
	s_nop 0
	s_nop 0
	v_ashrrev_i32_e32 v131, 31, v130
	v_pk_mul_f32 v[172:173], v[128:129], v[0:1] op_sel_hi:[1,0]
	v_pk_mul_f32 v[170:171], v[126:127], v[0:1] op_sel_hi:[1,0]
	v_pk_mul_f32 v[156:157], v[124:125], v[0:1] op_sel_hi:[1,0]
	v_pk_mul_f32 v[158:159], v[122:123], v[0:1] op_sel_hi:[1,0]
	v_lshl_add_u64 v[122:123], v[130:131], 1, s[76:77]
	v_cmp_gt_u32_e32 vcc, 2, v183
	s_and_saveexec_b64 s[0:1], vcc
	s_movk_i32 s46, 0x1600
	v_readlane_b32 s34, v254, 40
	s_cbranch_execz .LBB0_111
	v_mul_u32_u24_e32 v0, 0x1600, v183
	v_lshlrev_b32_e32 v0, 1, v0
	v_cvt_pk_bf16_f32 v124, v170, v171
	v_cvt_pk_bf16_f32 v125, v172, v173
	v_lshl_add_u64 v[128:129], v[122:123], 0, v[0:1]
	v_cvt_pk_bf16_f32 v126, v158, v159
	v_cvt_pk_bf16_f32 v127, v156, v157
	global_store_dwordx2 v[128:129], v[124:125], off
	global_store_dwordx2 v[128:129], v[126:127], off offset:256
.LBB0_111:
	s_or_b64 exec, exec, s[0:1]
	v_ffbh_u32_e32 v0, v137
	v_min_u32_e32 v0, 32, v0
	v_lshlrev_b64 v[124:125], v0, v[136:137]
	v_min_u32_e32 v124, 1, v124
	v_or_b32_e32 v124, v125, v124
	v_cvt_f32_u32_e32 v124, v124
	v_sub_u32_e32 v0, 32, v0
	v_ldexp_f32 v0, v124, v0
	v_fmamk_f32 v0, v0, 0x2e800000, v210
	s_nop 1
	v_rsq_f32_e32 v0, v0
	s_nop 0
	s_nop 0
	v_pk_mul_f32 v[174:175], v[120:121], v[0:1] op_sel_hi:[1,0]
	v_pk_mul_f32 v[176:177], v[118:119], v[0:1] op_sel_hi:[1,0]
	v_pk_mul_f32 v[152:153], v[116:117], v[0:1] op_sel_hi:[1,0]
	v_pk_mul_f32 v[154:155], v[114:115], v[0:1] op_sel_hi:[1,0]
	v_cmp_lt_u32_e32 vcc, 13, v183
	s_and_saveexec_b64 s[0:1], vcc
	s_cbranch_execz .LBB0_113
	v_add_u32_e32 v0, -12, v183
	s_movk_i32 s5, 0x2c00
	v_cvt_pk_bf16_f32 v114, v176, v177
	v_cvt_pk_bf16_f32 v115, v174, v175
	v_mad_u64_u32 v[118:119], s[28:29], v0, s5, v[122:123]
	v_cvt_pk_bf16_f32 v116, v154, v155
	v_cvt_pk_bf16_f32 v117, v152, v153
	global_store_dwordx2 v[118:119], v[114:115], off
	global_store_dwordx2 v[118:119], v[116:117], off offset:256
.LBB0_113:
	s_or_b64 exec, exec, s[0:1]
	v_ffbh_u32_e32 v0, v135
	v_min_u32_e32 v0, 32, v0
	v_lshlrev_b64 v[114:115], v0, v[134:135]
	v_min_u32_e32 v114, 1, v114
	v_or_b32_e32 v114, v115, v114
	v_cvt_f32_u32_e32 v114, v114
	v_sub_u32_e32 v0, 32, v0
	s_lshl_b32 s5, s78, 7
	v_add_u32_e32 v180, s5, v130
	v_ldexp_f32 v0, v114, v0
	v_fmamk_f32 v0, v0, 0x2e800000, v210
	s_nop 0
	v_rsq_f32_e32 v0, v0
	s_nop 0
	s_nop 0
	v_mov_b32_e32 v178, v0
	v_ffbh_u32_e32 v0, v133
	v_min_u32_e32 v0, 32, v0
	v_pk_mul_f32 v[186:187], v[110:111], v[178:179] op_sel_hi:[1,0]
	v_lshlrev_b64 v[110:111], v0, v[132:133]
	v_min_u32_e32 v110, 1, v110
	v_or_b32_e32 v110, v111, v110
	v_cvt_f32_u32_e32 v110, v110
	v_sub_u32_e32 v0, 32, v0
	v_pk_mul_f32 v[184:185], v[112:113], v[178:179] op_sel_hi:[1,0]
	v_ldexp_f32 v0, v110, v0
	v_fmamk_f32 v0, v0, 0x2e800000, v210
	s_nop 0
	v_rsq_f32_e32 v0, v0
	s_nop 0
	s_nop 0
	v_mov_b32_e32 v182, v0
	v_pk_mul_f32 v[188:189], v[108:109], v[182:183] op_sel_hi:[1,0]
	v_pk_mul_f32 v[198:199], v[106:107], v[182:183] op_sel_hi:[1,0]
	v_ashrrev_i32_e32 v181, 31, v180
	v_lshlrev_b64 v[118:119], 2, v[180:181]
	v_lshl_add_u64 v[106:107], s[44:45], 0, v[118:119]
	v_lshl_add_u64 v[108:109], s[60:61], 0, v[118:119]
	global_load_dwordx4 v[122:125], v[106:107], off
	global_load_dwordx4 v[126:129], v[108:109], off
	v_lshl_add_u64 v[106:107], s[2:3], 0, v[118:119]
	global_load_dwordx4 v[130:133], v[106:107], off
	v_lshl_add_u64 v[106:107], s[48:49], 0, v[118:119]
	global_load_dwordx4 v[134:137], v[106:107], off
	s_nop 1
	v_cmp_lt_u32_e32 vcc, 1, v183
	v_mov_b32_dpp v206, v170 row_ror:1 row_mask:0xf bank_mask:0xf
	v_mov_b32_dpp v204, v170 row_ror:2 row_mask:0xf bank_mask:0xf
	v_mov_b32_dpp v207, v171 row_ror:1 row_mask:0xf bank_mask:0xf
	v_mov_b32_dpp v205, v171 row_ror:2 row_mask:0xf bank_mask:0xf
	v_mov_b32_dpp v202, v172 row_ror:1 row_mask:0xf bank_mask:0xf
	v_mov_b32_dpp v200, v172 row_ror:2 row_mask:0xf bank_mask:0xf
	v_mov_b32_dpp v203, v173 row_ror:1 row_mask:0xf bank_mask:0xf
	v_mov_b32_dpp v201, v173 row_ror:2 row_mask:0xf bank_mask:0xf
	v_mov_b32_dpp v241, v186 row_ror:1 row_mask:0xf bank_mask:0xf
	v_mov_b32_dpp v240, v186 row_ror:2 row_mask:0xf bank_mask:0xf
	v_mov_b32_dpp v245, v187 row_ror:1 row_mask:0xf bank_mask:0xf
	v_mov_b32_dpp v244, v187 row_ror:2 row_mask:0xf bank_mask:0xf
	v_mov_b32_dpp v229, v184 row_ror:1 row_mask:0xf bank_mask:0xf
	v_mov_b32_dpp v228, v184 row_ror:2 row_mask:0xf bank_mask:0xf
	v_mov_b32_dpp v235, v185 row_ror:1 row_mask:0xf bank_mask:0xf
	v_mov_b32_dpp v233, v185 row_ror:2 row_mask:0xf bank_mask:0xf
	v_mov_b32_dpp v234, v198 row_ror:1 row_mask:0xf bank_mask:0xf
	v_mov_b32_dpp v231, v198 row_ror:2 row_mask:0xf bank_mask:0xf
	v_mov_b32_dpp v239, v199 row_ror:1 row_mask:0xf bank_mask:0xf
	v_mov_b32_dpp v237, v199 row_ror:2 row_mask:0xf bank_mask:0xf
	v_mov_b32_dpp v151, v188 row_ror:1 row_mask:0xf bank_mask:0xf
	v_mov_b32_dpp v0, v188 row_ror:2 row_mask:0xf bank_mask:0xf
	v_mov_b32_dpp v227, v189 row_ror:1 row_mask:0xf bank_mask:0xf
	v_mov_b32_dpp v213, v189 row_ror:2 row_mask:0xf bank_mask:0xf
	v_mov_b32_dpp v243, v176 row_ror:1 row_mask:0xf bank_mask:0xf
	v_mov_b32_dpp v242, v176 row_ror:2 row_mask:0xf bank_mask:0xf
	v_mov_b32_dpp v247, v177 row_ror:1 row_mask:0xf bank_mask:0xf
	v_mov_b32_dpp v246, v177 row_ror:2 row_mask:0xf bank_mask:0xf
	v_mov_b32_dpp v232, v174 row_ror:1 row_mask:0xf bank_mask:0xf
	v_mov_b32_dpp v230, v174 row_ror:2 row_mask:0xf bank_mask:0xf
	v_mov_b32_dpp v238, v175 row_ror:1 row_mask:0xf bank_mask:0xf
	v_mov_b32_dpp v236, v175 row_ror:2 row_mask:0xf bank_mask:0xf
	v_lshl_add_u64 v[106:107], s[96:97], 0, v[118:119]
	v_lshl_add_u64 v[108:109], s[62:63], 0, v[118:119]
	global_load_dwordx4 v[114:117], v[106:107], off
	global_load_dwordx4 v[110:113], v[108:109], off
	v_lshl_add_u64 v[106:107], s[64:65], 0, v[118:119]
	v_lshl_add_u64 v[118:119], s[66:67], 0, v[118:119]
	global_load_dwordx4 v[106:109], v[106:107], off
	s_nop 1
	global_load_dwordx4 v[118:121], v[118:119], off
	s_nop 1
	v_mov_b32_dpp v190, v158 row_ror:1 row_mask:0xf bank_mask:0xf
	v_mov_b32_dpp v194, v158 row_ror:2 row_mask:0xf bank_mask:0xf
	v_mov_b32_dpp v191, v159 row_ror:1 row_mask:0xf bank_mask:0xf
	v_mov_b32_dpp v195, v159 row_ror:2 row_mask:0xf bank_mask:0xf
	v_mov_b32_dpp v192, v156 row_ror:1 row_mask:0xf bank_mask:0xf
	v_mov_b32_dpp v196, v156 row_ror:2 row_mask:0xf bank_mask:0xf
	v_mov_b32_dpp v193, v157 row_ror:1 row_mask:0xf bank_mask:0xf
	v_mov_b32_dpp v197, v157 row_ror:2 row_mask:0xf bank_mask:0xf
	s_and_saveexec_b64 s[0:1], vcc
	s_mov_b32 s50, 0x20000
	s_mov_b32 s47, 0xbfb8aa3b
	s_cbranch_execz .Lcg_skip0
	s_waitcnt vmcnt(4)
	v_pk_fma_f32 v[248:249], v[124:125], v[200:201], v[136:137]
	s_nop 0
	v_pk_fma_f32 v[248:249], v[128:129], v[202:203], v[248:249]
	s_nop 0
	v_pk_fma_f32 v[172:173], v[172:173], v[132:133], v[248:249]
	v_pk_fma_f32 v[248:249], v[122:123], v[204:205], v[134:135]
	v_pk_fma_f32 v[248:249], v[126:127], v[206:207], v[248:249]
	v_pk_fma_f32 v[170:171], v[170:171], v[130:131], v[248:249]
	v_pk_mul_f32 v[248:249], v[170:171], s[98:99] op_sel_hi:[1,0]
	v_pk_mul_f32 v[250:251], v[172:173], s[98:99] op_sel_hi:[1,0]
	v_exp_f32_e32 v248, v248
	v_exp_f32_e32 v249, v249
	v_exp_f32_e32 v250, v250
	v_exp_f32_e32 v251, v251
	v_pk_add_f32 v[248:249], v[248:249], 1.0 op_sel_hi:[1,0]
	v_pk_add_f32 v[250:251], v[250:251], 1.0 op_sel_hi:[1,0]
	v_rcp_f32_e32 v248, v248
	v_rcp_f32_e32 v249, v249
	v_rcp_f32_e32 v250, v250
	v_rcp_f32_e32 v251, v251
	v_pk_mul_f32 v[170:171], v[170:171], v[248:249]
	v_pk_mul_f32 v[172:173], v[172:173], v[250:251]
	s_waitcnt vmcnt(0)
	v_pk_fma_f32 v[248:249], v[116:117], v[196:197], v[120:121]
	v_pk_fma_f32 v[250:251], v[114:115], v[194:195], v[118:119]
	v_pk_fma_f32 v[248:249], v[112:113], v[192:193], v[248:249]
	v_pk_fma_f32 v[250:251], v[110:111], v[190:191], v[250:251]
	v_pk_fma_f32 v[156:157], v[156:157], v[108:109], v[248:249]
	v_pk_fma_f32 v[158:159], v[158:159], v[106:107], v[250:251]
	v_pk_mul_f32 v[156:157], v[172:173], v[156:157]
	v_pk_mul_f32 v[158:159], v[170:171], v[158:159]
	s_nop 0
	v_cvt_pk_bf16_f32 v158, v158, v159
	v_cvt_pk_bf16_f32 v159, v156, v157
	v_mov_b64_e32 v[156:157], s[36:37]
	v_mad_i64_i32 v[156:157], s[28:29], v150, s46, v[156:157]
	v_lshl_add_u64 v[156:157], v[180:181], 1, v[156:157]
	global_store_dwordx2 v[156:157], v[158:159], off
.LBB0_115:
	s_or_b64 exec, exec, s[0:1]
	v_cmp_eq_u32_e64 s[42:43], 0, v183
	v_cndmask_b32_e32 v159, v205, v244, vcc
	v_cndmask_b32_e32 v158, v204, v240, vcc
	v_cndmask_b32_e64 v157, v245, v207, s[42:43]
	v_cndmask_b32_e64 v156, v241, v206, s[42:43]
	s_waitcnt vmcnt(4)
	v_pk_fma_f32 v[158:159], v[122:123], v[158:159], v[134:135]
	v_cndmask_b32_e32 v173, v201, v233, vcc
	v_cndmask_b32_e32 v172, v200, v228, vcc
	v_pk_fma_f32 v[156:157], v[126:127], v[156:157], v[158:159]
	v_cndmask_b32_e64 v171, v235, v203, s[42:43]
	v_cndmask_b32_e64 v170, v229, v202, s[42:43]
	v_pk_fma_f32 v[172:173], v[124:125], v[172:173], v[136:137]
	v_pk_fma_f32 v[156:157], v[186:187], v[130:131], v[156:157]
	v_pk_fma_f32 v[170:171], v[128:129], v[170:171], v[172:173]
	v_cndmask_b32_e32 v187, v244, v237, vcc
	v_cndmask_b32_e32 v186, v240, v231, vcc
	v_pk_fma_f32 v[170:171], v[184:185], v[132:133], v[170:171]
	v_cndmask_b32_e64 v185, v239, v245, s[42:43]
	v_cndmask_b32_e64 v184, v234, v241, s[42:43]
	v_pk_fma_f32 v[186:187], v[122:123], v[186:187], v[134:135]
	v_cndmask_b32_e32 v201, v233, v213, vcc
	v_pk_fma_f32 v[184:185], v[126:127], v[184:185], v[186:187]
	v_cndmask_b32_e32 v200, v228, v0, vcc
	v_pk_fma_f32 v[184:185], v[198:199], v[130:131], v[184:185]
	v_cndmask_b32_e64 v199, v227, v235, s[42:43]
	v_cndmask_b32_e64 v198, v151, v229, s[42:43]
	v_pk_fma_f32 v[200:201], v[124:125], v[200:201], v[136:137]
	v_cndmask_b32_e32 v203, v237, v246, vcc
	v_cndmask_b32_e32 v202, v231, v242, vcc
	v_pk_fma_f32 v[198:199], v[128:129], v[198:199], v[200:201]
	v_cndmask_b32_e64 v201, v247, v239, s[42:43]
	v_cndmask_b32_e64 v200, v243, v234, s[42:43]
	v_pk_fma_f32 v[122:123], v[122:123], v[202:203], v[134:135]
	v_cndmask_b32_e32 v135, v213, v236, vcc
	v_pk_fma_f32 v[122:123], v[126:127], v[200:201], v[122:123]
	v_cndmask_b32_e32 v134, v0, v230, vcc
	v_pk_fma_f32 v[122:123], v[176:177], v[130:131], v[122:123]
	v_cndmask_b32_e64 v131, v238, v227, s[42:43]
	v_cndmask_b32_e64 v130, v232, v151, s[42:43]
	v_pk_fma_f32 v[124:125], v[124:125], v[134:135], v[136:137]
	v_pk_fma_f32 v[124:125], v[128:129], v[130:131], v[124:125]
	v_mov_b32_e32 v179, v178
	v_pk_fma_f32 v[124:125], v[174:175], v[132:133], v[124:125]
	v_mov_b32_e32 v183, v182
	v_mov_b32_e32 v130, v178
	v_mov_b32_e32 v131, v178
	v_pk_mul_f32 v[104:105], v[104:105], v[130:131]
	v_pk_mul_f32 v[102:103], v[102:103], v[178:179]
	v_pk_mul_f32 v[98:99], v[98:99], v[182:183]
	s_nop 1
	v_mov_b32_e32 v130, v182
	v_mov_b32_e32 v131, v182
	s_nop 1
	v_mov_b32_dpp v177, v102 row_ror:2 row_mask:0xf bank_mask:0xf
	s_nop 1
	v_mov_b32_dpp v179, v103 row_ror:2 row_mask:0xf bank_mask:0xf
	s_nop 1
	v_mov_b32_dpp v183, v104 row_ror:2 row_mask:0xf bank_mask:0xf
	s_nop 1
	v_mov_b32_dpp v201, v105 row_ror:2 row_mask:0xf bank_mask:0xf
	v_pk_fma_f32 v[188:189], v[188:189], v[132:133], v[198:199]
	v_pk_mul_f32 v[100:101], v[100:101], v[130:131]
	v_mov_b32_dpp v176, v102 row_ror:1 row_mask:0xf bank_mask:0xf
	v_mov_b32_dpp v178, v103 row_ror:1 row_mask:0xf bank_mask:0xf
	v_mov_b32_dpp v182, v104 row_ror:1 row_mask:0xf bank_mask:0xf
	v_mov_b32_dpp v200, v105 row_ror:1 row_mask:0xf bank_mask:0xf
	v_cndmask_b32_e32 v130, v194, v177, vcc
	v_cndmask_b32_e32 v131, v195, v179, vcc
	v_cndmask_b32_e32 v132, v196, v183, vcc
	v_cndmask_b32_e32 v133, v197, v201, vcc
	v_cndmask_b32_e64 v134, v176, v190, s[42:43]
	v_cndmask_b32_e64 v135, v178, v191, s[42:43]
	v_cndmask_b32_e64 v136, v182, v192, s[42:43]
	v_cndmask_b32_e64 v137, v200, v193, s[42:43]
	s_waitcnt vmcnt(1)
	v_pk_fma_f32 v[132:133], v[116:117], v[132:133], v[120:121]
	v_pk_fma_f32 v[130:131], v[114:115], v[130:131], v[118:119]
	v_pk_fma_f32 v[132:133], v[112:113], v[136:137], v[132:133]
	v_pk_fma_f32 v[130:131], v[110:111], v[134:135], v[130:131]
	v_or_b32_e32 v0, 16, v150
	v_or_b32_e32 v174, 32, v150
	v_or_b32_e32 v175, 48, v150
	v_pk_mul_f32 v[158:159], v[156:157], s[98:99] op_sel_hi:[1,0]
	v_pk_mul_f32 v[172:173], v[170:171], s[98:99] op_sel_hi:[1,0]
	v_exp_f32_e32 v158, v158
	v_exp_f32_e32 v159, v159
	v_exp_f32_e32 v172, v172
	v_exp_f32_e32 v173, v173
	v_pk_add_f32 v[158:159], v[158:159], 1.0 op_sel_hi:[1,0]
	v_pk_add_f32 v[172:173], v[172:173], 1.0 op_sel_hi:[1,0]
	v_rcp_f32_e32 v158, v158
	v_rcp_f32_e32 v159, v159
	v_rcp_f32_e32 v172, v172
	v_rcp_f32_e32 v173, v173
	v_pk_mul_f32 v[150:151], v[156:157], v[158:159]
	v_pk_mul_f32 v[156:157], v[170:171], v[172:173]
	v_pk_fma_f32 v[104:105], v[104:105], v[108:109], v[132:133]
	v_pk_fma_f32 v[102:103], v[102:103], v[106:107], v[130:131]
	v_pk_mul_f32 v[104:105], v[156:157], v[104:105]
	v_pk_mul_f32 v[102:103], v[150:151], v[102:103]
	v_cvt_pk_bf16_f32 v102, v102, v103
	v_cvt_pk_bf16_f32 v103, v104, v105
	v_mov_b64_e32 v[104:105], s[36:37]
	v_mad_i64_i32 v[130:131], s[0:1], v0, s46, v[104:105]
	v_lshlrev_b64 v[132:133], 1, v[180:181]
	s_nop 1
	v_lshl_add_u64 v[130:131], v[130:131], 0, v[132:133]
	s_nop 1
	v_mov_b32_dpp v158, v98 row_ror:2 row_mask:0xf bank_mask:0xf
	s_nop 1
	v_mov_b32_dpp v170, v99 row_ror:2 row_mask:0xf bank_mask:0xf
	s_nop 1
	v_mov_b32_dpp v172, v100 row_ror:2 row_mask:0xf bank_mask:0xf
	s_nop 1
	v_mov_b32_dpp v180, v101 row_ror:2 row_mask:0xf bank_mask:0xf
	global_store_dwordx2 v[130:131], v[102:103], off
	v_mov_b32_dpp v0, v98 row_ror:1 row_mask:0xf bank_mask:0xf
	v_mov_b32_dpp v159, v99 row_ror:1 row_mask:0xf bank_mask:0xf
	v_mov_b32_dpp v171, v100 row_ror:1 row_mask:0xf bank_mask:0xf
	v_mov_b32_dpp v173, v101 row_ror:1 row_mask:0xf bank_mask:0xf
	v_cndmask_b32_e32 v102, v177, v158, vcc
	v_cndmask_b32_e32 v103, v179, v170, vcc
	v_cndmask_b32_e32 v130, v183, v172, vcc
	v_cndmask_b32_e32 v131, v201, v180, vcc
	v_cndmask_b32_e64 v134, v0, v176, s[42:43]
	v_cndmask_b32_e64 v135, v159, v178, s[42:43]
	v_cndmask_b32_e64 v136, v171, v182, s[42:43]
	v_cndmask_b32_e64 v137, v173, v200, s[42:43]
	v_pk_fma_f32 v[130:131], v[116:117], v[130:131], v[120:121]
	v_pk_fma_f32 v[102:103], v[114:115], v[102:103], v[118:119]
	v_pk_fma_f32 v[130:131], v[112:113], v[136:137], v[130:131]
	v_pk_fma_f32 v[102:103], v[110:111], v[134:135], v[102:103]
	v_pk_mul_f32 v[186:187], v[184:185], s[98:99] op_sel_hi:[1,0]
	v_pk_mul_f32 v[198:199], v[188:189], s[98:99] op_sel_hi:[1,0]
	v_exp_f32_e32 v186, v186
	v_exp_f32_e32 v187, v187
	v_exp_f32_e32 v198, v198
	v_exp_f32_e32 v199, v199
	v_pk_add_f32 v[186:187], v[186:187], 1.0 op_sel_hi:[1,0]
	v_pk_add_f32 v[198:199], v[198:199], 1.0 op_sel_hi:[1,0]
	v_rcp_f32_e32 v186, v186
	v_rcp_f32_e32 v187, v187
	v_rcp_f32_e32 v198, v198
	v_rcp_f32_e32 v199, v199
	v_pk_mul_f32 v[150:151], v[184:185], v[186:187]
	v_pk_mul_f32 v[156:157], v[188:189], v[198:199]
	v_pk_fma_f32 v[100:101], v[100:101], v[108:109], v[130:131]
	v_pk_fma_f32 v[98:99], v[98:99], v[106:107], v[102:103]
	v_pk_mul_f32 v[100:101], v[156:157], v[100:101]
	v_pk_mul_f32 v[98:99], v[150:151], v[98:99]
	v_cvt_pk_bf16_f32 v98, v98, v99
	v_cvt_pk_bf16_f32 v99, v100, v101
	v_mad_i64_i32 v[100:101], s[0:1], v174, s46, v[104:105]
	v_lshl_add_u64 v[100:101], v[100:101], 0, v[132:133]
	global_store_dwordx2 v[100:101], v[98:99], off
	s_nop 1
	s_nop 1
	v_mov_b32_dpp v98, v154 row_ror:2 row_mask:0xf bank_mask:0xf
	s_nop 1
	v_mov_b32_dpp v99, v155 row_ror:2 row_mask:0xf bank_mask:0xf
	s_nop 1
	v_mov_b32_dpp v100, v152 row_ror:2 row_mask:0xf bank_mask:0xf
	s_nop 1
	v_mov_b32_dpp v101, v153 row_ror:2 row_mask:0xf bank_mask:0xf
	v_mov_b32_dpp v102, v154 row_ror:1 row_mask:0xf bank_mask:0xf
	v_mov_b32_dpp v103, v155 row_ror:1 row_mask:0xf bank_mask:0xf
	v_mov_b32_dpp v130, v152 row_ror:1 row_mask:0xf bank_mask:0xf
	v_mov_b32_dpp v131, v153 row_ror:1 row_mask:0xf bank_mask:0xf
	v_cndmask_b32_e32 v98, v158, v98, vcc
	v_cndmask_b32_e32 v99, v170, v99, vcc
	v_cndmask_b32_e32 v100, v172, v100, vcc
	v_cndmask_b32_e32 v101, v180, v101, vcc
	v_cndmask_b32_e64 v102, v102, v0, s[42:43]
	v_cndmask_b32_e64 v103, v103, v159, s[42:43]
	v_cndmask_b32_e64 v130, v130, v171, s[42:43]
	v_cndmask_b32_e64 v131, v131, v173, s[42:43]
	v_pk_fma_f32 v[98:99], v[114:115], v[98:99], v[118:119]
	v_pk_fma_f32 v[100:101], v[116:117], v[100:101], v[120:121]
	v_pk_fma_f32 v[98:99], v[110:111], v[102:103], v[98:99]
	v_pk_fma_f32 v[100:101], v[112:113], v[130:131], v[100:101]
	v_pk_mul_f32 v[126:127], v[122:123], s[98:99] op_sel_hi:[1,0]
	v_pk_mul_f32 v[128:129], v[124:125], s[98:99] op_sel_hi:[1,0]
	v_exp_f32_e32 v126, v126
	v_exp_f32_e32 v127, v127
	v_exp_f32_e32 v128, v128
	v_exp_f32_e32 v129, v129
	v_pk_add_f32 v[126:127], v[126:127], 1.0 op_sel_hi:[1,0]
	v_pk_add_f32 v[128:129], v[128:129], 1.0 op_sel_hi:[1,0]
	v_rcp_f32_e32 v126, v126
	v_rcp_f32_e32 v127, v127
	v_rcp_f32_e32 v128, v128
	v_rcp_f32_e32 v129, v129
	v_pk_mul_f32 v[122:123], v[122:123], v[126:127]
	v_pk_mul_f32 v[124:125], v[124:125], v[128:129]
	v_pk_fma_f32 v[98:99], v[154:155], v[106:107], v[98:99]
	v_pk_fma_f32 v[100:101], v[152:153], v[108:109], v[100:101]
	v_pk_mul_f32 v[98:99], v[122:123], v[98:99]
	v_pk_mul_f32 v[100:101], v[124:125], v[100:101]
	v_cvt_pk_bf16_f32 v98, v98, v99
	s_nop 0
	v_cvt_pk_bf16_f32 v99, v100, v101
	v_mad_i64_i32 v[100:101], s[0:1], v175, s46, v[104:105]
	v_lshl_add_u64 v[100:101], v[100:101], 0, v[132:133]
	global_store_dwordx2 v[100:101], v[98:99], off
	s_add_i32 s0, s6, 2
	v_and_b32_e32 v129, 15, v226
	v_or_b32_e32 v106, s4, v129
	v_ashrrev_i32_e32 v107, 31, v106
	v_lshl_add_u64 v[104:105], v[106:107], 3, s[38:39]
	global_load_dwordx2 v[108:109], v[104:105], off offset:1024
	global_load_dwordx2 v[102:103], v[104:105], off offset:1152
	global_load_dwordx2 v[100:101], v[104:105], off offset:1280
	s_nop 0
	global_load_dwordx2 v[104:105], v[104:105], off offset:1408
	v_ashrrev_i32_e32 v0, 1, v226
	v_and_b32_e32 v0, -8, v0
	v_add_u32_e32 v98, s21, v0
	s_mul_hi_i32 s1, s0, 0xb000
	s_mul_i32 s0, s0, 0xb000
	s_add_u32 s0, s18, s0
	s_addc_u32 s1, s19, s1
	s_add_u32 s78, s0, s80
	s_addc_u32 s79, s1, s81
	s_waitcnt vmcnt(3)
	v_ffbh_u32_e32 v0, v109
	v_min_u32_e32 v0, 32, v0
	v_lshlrev_b64 v[108:109], v0, v[108:109]
	v_min_u32_e32 v99, 1, v108
	v_or_b32_e32 v99, v109, v99
	v_cvt_f32_u32_e32 v99, v99
	v_sub_u32_e32 v0, 32, v0
	v_ldexp_f32 v0, v99, v0
	v_fmamk_f32 v0, v0, 0x2e800000, v210
	s_nop 0
	v_rsq_f32_e32 v0, v0
	s_nop 0
	s_nop 0
	v_ashrrev_i32_e32 v99, 31, v98
	v_pk_mul_f32 v[118:119], v[96:97], v[0:1] op_sel_hi:[1,0]
	v_pk_mul_f32 v[116:117], v[94:95], v[0:1] op_sel_hi:[1,0]
	v_pk_mul_f32 v[112:113], v[92:93], v[0:1] op_sel_hi:[1,0]
	v_pk_mul_f32 v[114:115], v[90:91], v[0:1] op_sel_hi:[1,0]
	v_lshl_add_u64 v[90:91], v[98:99], 1, s[78:79]
	v_cmp_gt_u32_e32 vcc, 2, v129
	s_and_saveexec_b64 s[0:1], vcc
	s_cbranch_execz .LBB0_117
	v_mul_u32_u24_e32 v0, 0x1600, v129
	v_lshlrev_b32_e32 v0, 1, v0
	v_cvt_pk_bf16_f32 v92, v116, v117
	v_cvt_pk_bf16_f32 v93, v118, v119
	v_lshl_add_u64 v[96:97], v[90:91], 0, v[0:1]
	v_cvt_pk_bf16_f32 v94, v114, v115
	v_cvt_pk_bf16_f32 v95, v112, v113
	global_store_dwordx2 v[96:97], v[92:93], off
	global_store_dwordx2 v[96:97], v[94:95], off offset:256
.LBB0_117:
	s_or_b64 exec, exec, s[0:1]
	s_waitcnt vmcnt(0)
	v_ffbh_u32_e32 v0, v105
	v_min_u32_e32 v0, 32, v0
	v_lshlrev_b64 v[92:93], v0, v[104:105]
	v_min_u32_e32 v92, 1, v92
	v_or_b32_e32 v92, v93, v92
	v_cvt_f32_u32_e32 v92, v92
	v_sub_u32_e32 v0, 32, v0
	v_ldexp_f32 v0, v92, v0
	v_fmamk_f32 v0, v0, 0x2e800000, v210
	s_nop 1
	v_rsq_f32_e32 v0, v0
	s_nop 0
	s_nop 0
	v_pk_mul_f32 v[120:121], v[88:89], v[0:1] op_sel_hi:[1,0]
	v_pk_mul_f32 v[122:123], v[86:87], v[0:1] op_sel_hi:[1,0]
	v_pk_mul_f32 v[108:109], v[84:85], v[0:1] op_sel_hi:[1,0]
	v_pk_mul_f32 v[110:111], v[82:83], v[0:1] op_sel_hi:[1,0]
	v_cmp_lt_u32_e32 vcc, 13, v129
	s_and_saveexec_b64 s[0:1], vcc
	s_cbranch_execz .LBB0_119
	v_add_u32_e32 v0, -12, v129
	s_movk_i32 s6, 0x2c00
	v_cvt_pk_bf16_f32 v82, v122, v123
	v_cvt_pk_bf16_f32 v83, v120, v121
	v_mad_u64_u32 v[86:87], s[6:7], v0, s6, v[90:91]
	v_cvt_pk_bf16_f32 v84, v110, v111
	v_cvt_pk_bf16_f32 v85, v108, v109
	global_store_dwordx2 v[86:87], v[82:83], off
	global_store_dwordx2 v[86:87], v[84:85], off offset:256
.LBB0_119:
	s_or_b64 exec, exec, s[0:1]
	v_ffbh_u32_e32 v0, v103
	v_min_u32_e32 v0, 32, v0
	v_lshlrev_b64 v[82:83], v0, v[102:103]
	v_min_u32_e32 v82, 1, v82
	v_or_b32_e32 v82, v83, v82
	v_cvt_f32_u32_e32 v82, v82
	v_sub_u32_e32 v0, 32, v0
	v_add_u32_e32 v126, s5, v98
	v_ldexp_f32 v0, v82, v0
	v_fmamk_f32 v0, v0, 0x2e800000, v210
	s_nop 0
	v_rsq_f32_e32 v0, v0
	s_nop 0
	s_nop 0
	v_mov_b32_e32 v124, v0
	v_ffbh_u32_e32 v0, v101
	v_min_u32_e32 v0, 32, v0
	v_pk_mul_f32 v[132:133], v[78:79], v[124:125] op_sel_hi:[1,0]
	v_lshlrev_b64 v[78:79], v0, v[100:101]
	v_min_u32_e32 v78, 1, v78
	v_or_b32_e32 v78, v79, v78
	v_cvt_f32_u32_e32 v78, v78
	v_sub_u32_e32 v0, 32, v0
	v_pk_mul_f32 v[130:131], v[80:81], v[124:125] op_sel_hi:[1,0]
	v_ldexp_f32 v0, v78, v0
	v_fmamk_f32 v0, v0, 0x2e800000, v210
	s_nop 0
	v_rsq_f32_e32 v0, v0
	s_nop 0
	s_nop 0
	v_mov_b32_e32 v128, v0
	v_pk_mul_f32 v[134:135], v[76:77], v[128:129] op_sel_hi:[1,0]
	v_pk_mul_f32 v[156:157], v[74:75], v[128:129] op_sel_hi:[1,0]
	v_ashrrev_i32_e32 v127, 31, v126
	v_lshlrev_b64 v[86:87], 2, v[126:127]
	v_lshl_add_u64 v[74:75], s[44:45], 0, v[86:87]
	v_lshl_add_u64 v[76:77], s[60:61], 0, v[86:87]
	global_load_dwordx4 v[90:93], v[74:75], off
	global_load_dwordx4 v[94:97], v[76:77], off
	v_lshl_add_u64 v[74:75], s[2:3], 0, v[86:87]
	global_load_dwordx4 v[98:101], v[74:75], off
	v_lshl_add_u64 v[74:75], s[48:49], 0, v[86:87]
	global_load_dwordx4 v[102:105], v[74:75], off
	s_nop 1
	v_cmp_lt_u32_e32 vcc, 1, v129
	v_mov_b32_dpp v174, v116 row_ror:1 row_mask:0xf bank_mask:0xf
	v_mov_b32_dpp v172, v116 row_ror:2 row_mask:0xf bank_mask:0xf
	v_mov_b32_dpp v175, v117 row_ror:1 row_mask:0xf bank_mask:0xf
	v_mov_b32_dpp v173, v117 row_ror:2 row_mask:0xf bank_mask:0xf
	v_mov_b32_dpp v170, v118 row_ror:1 row_mask:0xf bank_mask:0xf
	v_mov_b32_dpp v158, v118 row_ror:2 row_mask:0xf bank_mask:0xf
	v_mov_b32_dpp v171, v119 row_ror:1 row_mask:0xf bank_mask:0xf
	v_mov_b32_dpp v159, v119 row_ror:2 row_mask:0xf bank_mask:0xf
	v_mov_b32_dpp v191, v132 row_ror:1 row_mask:0xf bank_mask:0xf
	v_mov_b32_dpp v190, v132 row_ror:2 row_mask:0xf bank_mask:0xf
	v_mov_b32_dpp v195, v133 row_ror:1 row_mask:0xf bank_mask:0xf
	v_mov_b32_dpp v194, v133 row_ror:2 row_mask:0xf bank_mask:0xf
	v_mov_b32_dpp v179, v130 row_ror:1 row_mask:0xf bank_mask:0xf
	v_mov_b32_dpp v178, v130 row_ror:2 row_mask:0xf bank_mask:0xf
	v_mov_b32_dpp v185, v131 row_ror:1 row_mask:0xf bank_mask:0xf
	v_mov_b32_dpp v183, v131 row_ror:2 row_mask:0xf bank_mask:0xf
	v_mov_b32_dpp v184, v156 row_ror:1 row_mask:0xf bank_mask:0xf
	v_mov_b32_dpp v181, v156 row_ror:2 row_mask:0xf bank_mask:0xf
	v_mov_b32_dpp v189, v157 row_ror:1 row_mask:0xf bank_mask:0xf
	v_mov_b32_dpp v187, v157 row_ror:2 row_mask:0xf bank_mask:0xf
	v_mov_b32_dpp v107, v134 row_ror:1 row_mask:0xf bank_mask:0xf
	v_mov_b32_dpp v0, v134 row_ror:2 row_mask:0xf bank_mask:0xf
	v_mov_b32_dpp v177, v135 row_ror:1 row_mask:0xf bank_mask:0xf
	v_mov_b32_dpp v176, v135 row_ror:2 row_mask:0xf bank_mask:0xf
	v_mov_b32_dpp v193, v122 row_ror:1 row_mask:0xf bank_mask:0xf
	v_mov_b32_dpp v192, v122 row_ror:2 row_mask:0xf bank_mask:0xf
	v_mov_b32_dpp v197, v123 row_ror:1 row_mask:0xf bank_mask:0xf
	v_mov_b32_dpp v196, v123 row_ror:2 row_mask:0xf bank_mask:0xf
	v_mov_b32_dpp v182, v120 row_ror:1 row_mask:0xf bank_mask:0xf
	v_mov_b32_dpp v180, v120 row_ror:2 row_mask:0xf bank_mask:0xf
	v_mov_b32_dpp v188, v121 row_ror:1 row_mask:0xf bank_mask:0xf
	v_mov_b32_dpp v186, v121 row_ror:2 row_mask:0xf bank_mask:0xf
	v_lshl_add_u64 v[74:75], s[96:97], 0, v[86:87]
	v_lshl_add_u64 v[76:77], s[62:63], 0, v[86:87]
	global_load_dwordx4 v[82:85], v[74:75], off
	global_load_dwordx4 v[78:81], v[76:77], off
	v_lshl_add_u64 v[74:75], s[64:65], 0, v[86:87]
	v_lshl_add_u64 v[86:87], s[66:67], 0, v[86:87]
	global_load_dwordx4 v[74:77], v[74:75], off
	s_nop 1
	global_load_dwordx4 v[86:89], v[86:87], off
	s_nop 1
	v_mov_b32_dpp v136, v114 row_ror:1 row_mask:0xf bank_mask:0xf
	v_mov_b32_dpp v152, v114 row_ror:2 row_mask:0xf bank_mask:0xf
	v_mov_b32_dpp v137, v115 row_ror:1 row_mask:0xf bank_mask:0xf
	v_mov_b32_dpp v153, v115 row_ror:2 row_mask:0xf bank_mask:0xf
	v_mov_b32_dpp v150, v112 row_ror:1 row_mask:0xf bank_mask:0xf
	v_mov_b32_dpp v154, v112 row_ror:2 row_mask:0xf bank_mask:0xf
	v_mov_b32_dpp v151, v113 row_ror:1 row_mask:0xf bank_mask:0xf
	v_mov_b32_dpp v155, v113 row_ror:2 row_mask:0xf bank_mask:0xf
	s_and_saveexec_b64 s[0:1], vcc
	s_cbranch_execz .Lcg_skip1
	s_waitcnt vmcnt(4)
	v_pk_fma_f32 v[198:199], v[92:93], v[158:159], v[104:105]
	s_nop 0
	v_pk_fma_f32 v[198:199], v[96:97], v[170:171], v[198:199]
	s_nop 0
	v_pk_fma_f32 v[118:119], v[118:119], v[100:101], v[198:199]
	v_pk_fma_f32 v[198:199], v[90:91], v[172:173], v[102:103]
	v_pk_fma_f32 v[198:199], v[94:95], v[174:175], v[198:199]
	v_pk_fma_f32 v[116:117], v[116:117], v[98:99], v[198:199]
	v_add_u32_e32 v125, 0x80, v106
	v_pk_mul_f32 v[198:199], v[116:117], s[98:99] op_sel_hi:[1,0]
	v_pk_mul_f32 v[200:201], v[118:119], s[98:99] op_sel_hi:[1,0]
	v_exp_f32_e32 v198, v198
	v_exp_f32_e32 v199, v199
	v_exp_f32_e32 v200, v200
	v_exp_f32_e32 v201, v201
	v_pk_add_f32 v[198:199], v[198:199], 1.0 op_sel_hi:[1,0]
	v_pk_add_f32 v[200:201], v[200:201], 1.0 op_sel_hi:[1,0]
	v_rcp_f32_e32 v198, v198
	v_rcp_f32_e32 v199, v199
	v_rcp_f32_e32 v200, v200
	v_rcp_f32_e32 v201, v201
	v_pk_mul_f32 v[116:117], v[116:117], v[198:199]
	v_pk_mul_f32 v[118:119], v[118:119], v[200:201]
	s_waitcnt vmcnt(0)
	v_pk_fma_f32 v[198:199], v[84:85], v[154:155], v[88:89]
	v_pk_fma_f32 v[200:201], v[82:83], v[152:153], v[86:87]
	v_pk_fma_f32 v[198:199], v[80:81], v[150:151], v[198:199]
	v_pk_fma_f32 v[200:201], v[78:79], v[136:137], v[200:201]
	v_pk_fma_f32 v[112:113], v[112:113], v[76:77], v[198:199]
	v_pk_fma_f32 v[114:115], v[114:115], v[74:75], v[200:201]
	v_pk_mul_f32 v[112:113], v[118:119], v[112:113]
	v_pk_mul_f32 v[114:115], v[116:117], v[114:115]
	s_nop 0
	v_cvt_pk_bf16_f32 v114, v114, v115
	v_cvt_pk_bf16_f32 v115, v112, v113
	v_mov_b64_e32 v[112:113], s[36:37]
	v_mad_i64_i32 v[112:113], s[6:7], v125, s46, v[112:113]
	v_lshl_add_u64 v[112:113], v[126:127], 1, v[112:113]
	global_store_dwordx2 v[112:113], v[114:115], off
.LBB0_121:
	s_or_b64 exec, exec, s[0:1]
	v_cmp_eq_u32_e64 s[42:43], 0, v129
	v_cndmask_b32_e32 v115, v173, v194, vcc
	v_cndmask_b32_e32 v114, v172, v190, vcc
	v_cndmask_b32_e64 v113, v195, v175, s[42:43]
	v_cndmask_b32_e64 v112, v191, v174, s[42:43]
	s_waitcnt vmcnt(4)
	v_pk_fma_f32 v[114:115], v[90:91], v[114:115], v[102:103]
	v_cndmask_b32_e32 v119, v159, v183, vcc
	v_cndmask_b32_e32 v118, v158, v178, vcc
	v_pk_fma_f32 v[112:113], v[94:95], v[112:113], v[114:115]
	v_cndmask_b32_e64 v117, v185, v171, s[42:43]
	v_cndmask_b32_e64 v116, v179, v170, s[42:43]
	v_pk_fma_f32 v[118:119], v[92:93], v[118:119], v[104:105]
	v_pk_fma_f32 v[112:113], v[132:133], v[98:99], v[112:113]
	v_pk_fma_f32 v[116:117], v[96:97], v[116:117], v[118:119]
	v_cndmask_b32_e32 v133, v194, v187, vcc
	v_cndmask_b32_e32 v132, v190, v181, vcc
	v_pk_fma_f32 v[116:117], v[130:131], v[100:101], v[116:117]
	v_cndmask_b32_e64 v131, v189, v195, s[42:43]
	v_cndmask_b32_e64 v130, v184, v191, s[42:43]
	v_pk_fma_f32 v[132:133], v[90:91], v[132:133], v[102:103]
	v_cndmask_b32_e32 v159, v183, v176, vcc
	v_pk_fma_f32 v[130:131], v[94:95], v[130:131], v[132:133]
	v_cndmask_b32_e32 v158, v178, v0, vcc
	v_pk_fma_f32 v[130:131], v[156:157], v[98:99], v[130:131]
	v_cndmask_b32_e64 v157, v177, v185, s[42:43]
	v_cndmask_b32_e64 v156, v107, v179, s[42:43]
	v_pk_fma_f32 v[158:159], v[92:93], v[158:159], v[104:105]
	v_cndmask_b32_e32 v171, v187, v196, vcc
	v_cndmask_b32_e32 v170, v181, v192, vcc
	v_pk_fma_f32 v[156:157], v[96:97], v[156:157], v[158:159]
	v_cndmask_b32_e64 v159, v197, v189, s[42:43]
	v_cndmask_b32_e64 v158, v193, v184, s[42:43]
	v_pk_fma_f32 v[90:91], v[90:91], v[170:171], v[102:103]
	v_cndmask_b32_e32 v103, v176, v186, vcc
	v_pk_fma_f32 v[90:91], v[94:95], v[158:159], v[90:91]
	v_cndmask_b32_e32 v102, v0, v180, vcc
	v_pk_fma_f32 v[90:91], v[122:123], v[98:99], v[90:91]
	v_cndmask_b32_e64 v99, v188, v177, s[42:43]
	v_cndmask_b32_e64 v98, v182, v107, s[42:43]
	v_pk_fma_f32 v[92:93], v[92:93], v[102:103], v[104:105]
	v_pk_fma_f32 v[92:93], v[96:97], v[98:99], v[92:93]
	v_mov_b32_e32 v125, v124
	v_pk_fma_f32 v[92:93], v[120:121], v[100:101], v[92:93]
	v_mov_b32_e32 v129, v128
	v_mov_b32_e32 v98, v124
	v_mov_b32_e32 v99, v124
	v_pk_mul_f32 v[72:73], v[72:73], v[98:99]
	v_pk_mul_f32 v[70:71], v[70:71], v[124:125]
	v_pk_mul_f32 v[66:67], v[66:67], v[128:129]
	s_nop 1
	v_mov_b32_e32 v98, v128
	v_mov_b32_e32 v99, v128
	s_nop 1
	v_mov_b32_dpp v123, v70 row_ror:2 row_mask:0xf bank_mask:0xf
	s_nop 1
	v_mov_b32_dpp v125, v71 row_ror:2 row_mask:0xf bank_mask:0xf
	s_nop 1
	v_mov_b32_dpp v129, v72 row_ror:2 row_mask:0xf bank_mask:0xf
	s_nop 1
	v_mov_b32_dpp v159, v73 row_ror:2 row_mask:0xf bank_mask:0xf
	v_pk_fma_f32 v[134:135], v[134:135], v[100:101], v[156:157]
	v_pk_mul_f32 v[68:69], v[68:69], v[98:99]
	v_mov_b32_dpp v122, v70 row_ror:1 row_mask:0xf bank_mask:0xf
	v_mov_b32_dpp v124, v71 row_ror:1 row_mask:0xf bank_mask:0xf
	v_mov_b32_dpp v128, v72 row_ror:1 row_mask:0xf bank_mask:0xf
	v_mov_b32_dpp v158, v73 row_ror:1 row_mask:0xf bank_mask:0xf
	v_cndmask_b32_e32 v98, v152, v123, vcc
	v_cndmask_b32_e32 v99, v153, v125, vcc
	v_cndmask_b32_e32 v100, v154, v129, vcc
	v_cndmask_b32_e32 v101, v155, v159, vcc
	v_cndmask_b32_e64 v102, v122, v136, s[42:43]
	v_cndmask_b32_e64 v103, v124, v137, s[42:43]
	v_cndmask_b32_e64 v104, v128, v150, s[42:43]
	v_cndmask_b32_e64 v105, v158, v151, s[42:43]
	s_waitcnt vmcnt(1)
	v_pk_fma_f32 v[100:101], v[84:85], v[100:101], v[88:89]
	v_pk_fma_f32 v[98:99], v[82:83], v[98:99], v[86:87]
	v_pk_fma_f32 v[100:101], v[80:81], v[104:105], v[100:101]
	v_pk_fma_f32 v[98:99], v[78:79], v[102:103], v[98:99]
	v_add_u32_e32 v0, 0x90, v106
	v_add_u32_e32 v120, 0xa0, v106
	v_add_u32_e32 v121, 0xb0, v106
	v_pk_mul_f32 v[114:115], v[112:113], s[98:99] op_sel_hi:[1,0]
	v_pk_mul_f32 v[118:119], v[116:117], s[98:99] op_sel_hi:[1,0]
	v_exp_f32_e32 v114, v114
	v_exp_f32_e32 v115, v115
	v_exp_f32_e32 v118, v118
	v_exp_f32_e32 v119, v119
	v_pk_add_f32 v[114:115], v[114:115], 1.0 op_sel_hi:[1,0]
	v_pk_add_f32 v[118:119], v[118:119], 1.0 op_sel_hi:[1,0]
	v_rcp_f32_e32 v114, v114
	v_rcp_f32_e32 v115, v115
	v_rcp_f32_e32 v118, v118
	v_rcp_f32_e32 v119, v119
	v_pk_mul_f32 v[106:107], v[112:113], v[114:115]
	v_pk_mul_f32 v[112:113], v[116:117], v[118:119]
	v_pk_fma_f32 v[72:73], v[72:73], v[76:77], v[100:101]
	v_pk_fma_f32 v[70:71], v[70:71], v[74:75], v[98:99]
	v_pk_mul_f32 v[72:73], v[112:113], v[72:73]
	v_pk_mul_f32 v[70:71], v[106:107], v[70:71]
	v_cvt_pk_bf16_f32 v70, v70, v71
	v_cvt_pk_bf16_f32 v71, v72, v73
	v_mov_b64_e32 v[72:73], s[36:37]
	v_mad_i64_i32 v[98:99], s[0:1], v0, s46, v[72:73]
	v_lshlrev_b64 v[100:101], 1, v[126:127]
	s_nop 1
	v_lshl_add_u64 v[98:99], v[98:99], 0, v[100:101]
	s_nop 1
	v_mov_b32_dpp v114, v66 row_ror:2 row_mask:0xf bank_mask:0xf
	s_nop 1
	v_mov_b32_dpp v116, v67 row_ror:2 row_mask:0xf bank_mask:0xf
	s_nop 1
	v_mov_b32_dpp v118, v68 row_ror:2 row_mask:0xf bank_mask:0xf
	s_nop 1
	v_mov_b32_dpp v126, v69 row_ror:2 row_mask:0xf bank_mask:0xf
	global_store_dwordx2 v[98:99], v[70:71], off
	v_mov_b32_dpp v0, v66 row_ror:1 row_mask:0xf bank_mask:0xf
	v_mov_b32_dpp v115, v67 row_ror:1 row_mask:0xf bank_mask:0xf
	v_mov_b32_dpp v117, v68 row_ror:1 row_mask:0xf bank_mask:0xf
	v_mov_b32_dpp v119, v69 row_ror:1 row_mask:0xf bank_mask:0xf
	v_cndmask_b32_e32 v70, v123, v114, vcc
	v_cndmask_b32_e32 v71, v125, v116, vcc
	v_cndmask_b32_e32 v98, v129, v118, vcc
	v_cndmask_b32_e32 v99, v159, v126, vcc
	v_cndmask_b32_e64 v102, v0, v122, s[42:43]
	v_cndmask_b32_e64 v103, v115, v124, s[42:43]
	v_cndmask_b32_e64 v104, v117, v128, s[42:43]
	v_cndmask_b32_e64 v105, v119, v158, s[42:43]
	v_pk_fma_f32 v[98:99], v[84:85], v[98:99], v[88:89]
	v_pk_fma_f32 v[70:71], v[82:83], v[70:71], v[86:87]
	v_pk_fma_f32 v[98:99], v[80:81], v[104:105], v[98:99]
	v_pk_fma_f32 v[70:71], v[78:79], v[102:103], v[70:71]
	v_pk_mul_f32 v[132:133], v[130:131], s[98:99] op_sel_hi:[1,0]
	v_pk_mul_f32 v[156:157], v[134:135], s[98:99] op_sel_hi:[1,0]
	v_exp_f32_e32 v132, v132
	v_exp_f32_e32 v133, v133
	v_exp_f32_e32 v156, v156
	v_exp_f32_e32 v157, v157
	v_pk_add_f32 v[132:133], v[132:133], 1.0 op_sel_hi:[1,0]
	v_pk_add_f32 v[156:157], v[156:157], 1.0 op_sel_hi:[1,0]
	v_rcp_f32_e32 v132, v132
	v_rcp_f32_e32 v133, v133
	v_rcp_f32_e32 v156, v156
	v_rcp_f32_e32 v157, v157
	v_pk_mul_f32 v[106:107], v[130:131], v[132:133]
	v_pk_mul_f32 v[112:113], v[134:135], v[156:157]
	v_pk_fma_f32 v[68:69], v[68:69], v[76:77], v[98:99]
	v_pk_fma_f32 v[66:67], v[66:67], v[74:75], v[70:71]
	v_pk_mul_f32 v[68:69], v[112:113], v[68:69]
	v_pk_mul_f32 v[66:67], v[106:107], v[66:67]
	v_cvt_pk_bf16_f32 v66, v66, v67
	v_cvt_pk_bf16_f32 v67, v68, v69
	v_mad_i64_i32 v[68:69], s[0:1], v120, s46, v[72:73]
	v_lshl_add_u64 v[68:69], v[68:69], 0, v[100:101]
	global_store_dwordx2 v[68:69], v[66:67], off
	s_nop 1
	s_nop 1
	v_mov_b32_dpp v66, v110 row_ror:2 row_mask:0xf bank_mask:0xf
	s_nop 1
	v_mov_b32_dpp v67, v111 row_ror:2 row_mask:0xf bank_mask:0xf
	s_nop 1
	v_mov_b32_dpp v68, v108 row_ror:2 row_mask:0xf bank_mask:0xf
	s_nop 1
	v_mov_b32_dpp v69, v109 row_ror:2 row_mask:0xf bank_mask:0xf
	v_mov_b32_dpp v70, v110 row_ror:1 row_mask:0xf bank_mask:0xf
	v_mov_b32_dpp v71, v111 row_ror:1 row_mask:0xf bank_mask:0xf
	v_mov_b32_dpp v98, v108 row_ror:1 row_mask:0xf bank_mask:0xf
	v_mov_b32_dpp v99, v109 row_ror:1 row_mask:0xf bank_mask:0xf
	v_cndmask_b32_e32 v66, v114, v66, vcc
	v_cndmask_b32_e32 v67, v116, v67, vcc
	v_cndmask_b32_e32 v68, v118, v68, vcc
	v_cndmask_b32_e32 v69, v126, v69, vcc
	v_cndmask_b32_e64 v70, v70, v0, s[42:43]
	v_cndmask_b32_e64 v71, v71, v115, s[42:43]
	v_cndmask_b32_e64 v98, v98, v117, s[42:43]
	v_cndmask_b32_e64 v99, v99, v119, s[42:43]
	v_pk_fma_f32 v[66:67], v[82:83], v[66:67], v[86:87]
	v_pk_fma_f32 v[68:69], v[84:85], v[68:69], v[88:89]
	v_pk_fma_f32 v[66:67], v[78:79], v[70:71], v[66:67]
	v_pk_fma_f32 v[68:69], v[80:81], v[98:99], v[68:69]
	v_pk_mul_f32 v[94:95], v[90:91], s[98:99] op_sel_hi:[1,0]
	v_pk_mul_f32 v[96:97], v[92:93], s[98:99] op_sel_hi:[1,0]
	v_exp_f32_e32 v94, v94
	v_exp_f32_e32 v95, v95
	v_exp_f32_e32 v96, v96
	v_exp_f32_e32 v97, v97
	v_pk_add_f32 v[94:95], v[94:95], 1.0 op_sel_hi:[1,0]
	v_pk_add_f32 v[96:97], v[96:97], 1.0 op_sel_hi:[1,0]
	v_rcp_f32_e32 v94, v94
	v_rcp_f32_e32 v95, v95
	v_rcp_f32_e32 v96, v96
	v_rcp_f32_e32 v97, v97
	v_pk_mul_f32 v[90:91], v[90:91], v[94:95]
	v_pk_mul_f32 v[92:93], v[92:93], v[96:97]
	v_pk_fma_f32 v[66:67], v[110:111], v[74:75], v[66:67]
	v_pk_fma_f32 v[68:69], v[108:109], v[76:77], v[68:69]
	v_pk_mul_f32 v[66:67], v[90:91], v[66:67]
	v_pk_mul_f32 v[68:69], v[92:93], v[68:69]
	v_cvt_pk_bf16_f32 v66, v66, v67
	s_nop 0
	v_cvt_pk_bf16_f32 v67, v68, v69
	v_mad_i64_i32 v[68:69], s[0:1], v121, s46, v[72:73]
	v_lshl_add_u64 v[68:69], v[68:69], 0, v[100:101]
	global_store_dwordx2 v[68:69], v[66:67], off
	s_nop 0
	v_and_b32_e32 v97, 15, v226
	v_or_b32_e32 v74, s4, v97
	v_ashrrev_i32_e32 v75, 31, v74
	v_lshl_add_u64 v[72:73], v[74:75], 3, s[38:39]
	global_load_dwordx2 v[76:77], v[72:73], off
	global_load_dwordx2 v[70:71], v[72:73], off offset:128
	global_load_dwordx2 v[68:69], v[72:73], off offset:256
	s_nop 0
	global_load_dwordx2 v[72:73], v[72:73], off offset:384
	v_ashrrev_i32_e32 v0, 1, v226
	v_and_b32_e32 v0, -8, v0
	v_add_u32_e32 v66, s21, v0
	s_waitcnt vmcnt(3)
	v_ffbh_u32_e32 v0, v77
	v_min_u32_e32 v0, 32, v0
	v_lshlrev_b64 v[76:77], v0, v[76:77]
	v_min_u32_e32 v67, 1, v76
	v_or_b32_e32 v67, v77, v67
	v_cvt_f32_u32_e32 v67, v67
	v_sub_u32_e32 v0, 32, v0
	v_ldexp_f32 v0, v67, v0
	v_fmamk_f32 v0, v0, 0x2e800000, v210
	s_nop 0
	v_rsq_f32_e32 v0, v0
	s_nop 0
	s_nop 0
	v_ashrrev_i32_e32 v67, 31, v66
	v_pk_mul_f32 v[92:93], v[64:65], v[0:1] op_sel_hi:[1,0]
	v_pk_mul_f32 v[90:91], v[62:63], v[0:1] op_sel_hi:[1,0]
	v_pk_mul_f32 v[86:87], v[60:61], v[0:1] op_sel_hi:[1,0]
	v_pk_mul_f32 v[88:89], v[58:59], v[0:1] op_sel_hi:[1,0]
	v_lshl_add_u64 v[58:59], v[66:67], 1, s[76:77]
	v_cmp_gt_u32_e32 vcc, 2, v97
	s_and_saveexec_b64 s[0:1], vcc
	s_cbranch_execz .LBB0_123
	v_mul_u32_u24_e32 v0, 0x1600, v97
	v_lshlrev_b32_e32 v0, 1, v0
	v_cvt_pk_bf16_f32 v60, v90, v91
	v_cvt_pk_bf16_f32 v61, v92, v93
	v_lshl_add_u64 v[64:65], v[58:59], 0, v[0:1]
	v_cvt_pk_bf16_f32 v62, v88, v89
	v_cvt_pk_bf16_f32 v63, v86, v87
	global_store_dwordx2 v[64:65], v[60:61], off offset:8
	global_store_dwordx2 v[64:65], v[62:63], off offset:264
.LBB0_123:
	s_or_b64 exec, exec, s[0:1]
	s_waitcnt vmcnt(0)
	v_ffbh_u32_e32 v0, v73
	v_min_u32_e32 v0, 32, v0
	v_lshlrev_b64 v[60:61], v0, v[72:73]
	v_min_u32_e32 v60, 1, v60
	v_or_b32_e32 v60, v61, v60
	v_cvt_f32_u32_e32 v60, v60
	v_sub_u32_e32 v0, 32, v0
	v_ldexp_f32 v0, v60, v0
	v_fmamk_f32 v0, v0, 0x2e800000, v210
	s_nop 1
	v_rsq_f32_e32 v0, v0
	s_nop 0
	s_nop 0
	v_pk_mul_f32 v[80:81], v[56:57], v[0:1] op_sel_hi:[1,0]
	v_pk_mul_f32 v[82:83], v[54:55], v[0:1] op_sel_hi:[1,0]
	v_pk_mul_f32 v[76:77], v[52:53], v[0:1] op_sel_hi:[1,0]
	v_pk_mul_f32 v[78:79], v[50:51], v[0:1] op_sel_hi:[1,0]
	v_cmp_lt_u32_e32 vcc, 13, v97
	s_and_saveexec_b64 s[0:1], vcc
	s_cbranch_execz .LBB0_125
	v_add_u32_e32 v0, -12, v97
	s_movk_i32 s6, 0x2c00
	v_cvt_pk_bf16_f32 v50, v82, v83
	v_cvt_pk_bf16_f32 v51, v80, v81
	v_mad_u64_u32 v[54:55], s[6:7], v0, s6, v[58:59]
	v_cvt_pk_bf16_f32 v52, v78, v79
	v_cvt_pk_bf16_f32 v53, v76, v77
	global_store_dwordx2 v[54:55], v[50:51], off offset:8
	global_store_dwordx2 v[54:55], v[52:53], off offset:264
.LBB0_125:
	s_or_b64 exec, exec, s[0:1]
	v_ffbh_u32_e32 v0, v71
	v_min_u32_e32 v0, 32, v0
	v_lshlrev_b64 v[50:51], v0, v[70:71]
	v_min_u32_e32 v50, 1, v50
	v_or_b32_e32 v50, v51, v50
	v_cvt_f32_u32_e32 v50, v50
	v_sub_u32_e32 v0, 32, v0
	s_or_b32 s5, s5, 4
	v_add_u32_e32 v94, s5, v66
	v_ldexp_f32 v0, v50, v0
	v_fmamk_f32 v0, v0, 0x2e800000, v210
	s_nop 0
	v_rsq_f32_e32 v0, v0
	s_nop 0
	s_nop 0
	v_mov_b32_e32 v84, v0
	v_ffbh_u32_e32 v0, v69
	v_min_u32_e32 v0, 32, v0
	v_pk_mul_f32 v[100:101], v[46:47], v[84:85] op_sel_hi:[1,0]
	v_lshlrev_b64 v[46:47], v0, v[68:69]
	v_min_u32_e32 v46, 1, v46
	v_or_b32_e32 v46, v47, v46
	v_cvt_f32_u32_e32 v46, v46
	v_sub_u32_e32 v0, 32, v0
	v_pk_mul_f32 v[98:99], v[48:49], v[84:85] op_sel_hi:[1,0]
	v_ldexp_f32 v0, v46, v0
	v_fmamk_f32 v0, v0, 0x2e800000, v210
	s_nop 0
	v_rsq_f32_e32 v0, v0
	s_nop 0
	s_nop 0
	v_mov_b32_e32 v96, v0
	v_pk_mul_f32 v[102:103], v[44:45], v[96:97] op_sel_hi:[1,0]
	v_pk_mul_f32 v[112:113], v[42:43], v[96:97] op_sel_hi:[1,0]
	v_ashrrev_i32_e32 v95, 31, v94
	v_lshlrev_b64 v[54:55], 2, v[94:95]
	v_lshl_add_u64 v[42:43], s[44:45], 0, v[54:55]
	v_lshl_add_u64 v[44:45], s[60:61], 0, v[54:55]
	global_load_dwordx4 v[58:61], v[42:43], off
	global_load_dwordx4 v[62:65], v[44:45], off
	v_lshl_add_u64 v[42:43], s[2:3], 0, v[54:55]
	global_load_dwordx4 v[66:69], v[42:43], off
	v_lshl_add_u64 v[42:43], s[48:49], 0, v[54:55]
	global_load_dwordx4 v[70:73], v[42:43], off
	s_nop 1
	v_cmp_lt_u32_e32 vcc, 1, v97
	v_mov_b32_dpp v120, v90 row_ror:1 row_mask:0xf bank_mask:0xf
	v_mov_b32_dpp v118, v90 row_ror:2 row_mask:0xf bank_mask:0xf
	v_mov_b32_dpp v121, v91 row_ror:1 row_mask:0xf bank_mask:0xf
	v_mov_b32_dpp v119, v91 row_ror:2 row_mask:0xf bank_mask:0xf
	v_mov_b32_dpp v116, v92 row_ror:1 row_mask:0xf bank_mask:0xf
	v_mov_b32_dpp v114, v92 row_ror:2 row_mask:0xf bank_mask:0xf
	v_mov_b32_dpp v117, v93 row_ror:1 row_mask:0xf bank_mask:0xf
	v_mov_b32_dpp v115, v93 row_ror:2 row_mask:0xf bank_mask:0xf
	v_mov_b32_dpp v137, v100 row_ror:1 row_mask:0xf bank_mask:0xf
	v_mov_b32_dpp v136, v100 row_ror:2 row_mask:0xf bank_mask:0xf
	v_mov_b32_dpp v153, v101 row_ror:1 row_mask:0xf bank_mask:0xf
	v_mov_b32_dpp v152, v101 row_ror:2 row_mask:0xf bank_mask:0xf
	v_mov_b32_dpp v125, v98 row_ror:1 row_mask:0xf bank_mask:0xf
	v_mov_b32_dpp v124, v98 row_ror:2 row_mask:0xf bank_mask:0xf
	v_mov_b32_dpp v131, v99 row_ror:1 row_mask:0xf bank_mask:0xf
	v_mov_b32_dpp v129, v99 row_ror:2 row_mask:0xf bank_mask:0xf
	v_mov_b32_dpp v130, v112 row_ror:1 row_mask:0xf bank_mask:0xf
	v_mov_b32_dpp v127, v112 row_ror:2 row_mask:0xf bank_mask:0xf
	v_mov_b32_dpp v135, v113 row_ror:1 row_mask:0xf bank_mask:0xf
	v_mov_b32_dpp v133, v113 row_ror:2 row_mask:0xf bank_mask:0xf
	v_mov_b32_dpp v75, v102 row_ror:1 row_mask:0xf bank_mask:0xf
	v_mov_b32_dpp v0, v102 row_ror:2 row_mask:0xf bank_mask:0xf
	v_mov_b32_dpp v123, v103 row_ror:1 row_mask:0xf bank_mask:0xf
	v_mov_b32_dpp v122, v103 row_ror:2 row_mask:0xf bank_mask:0xf
	v_mov_b32_dpp v151, v82 row_ror:1 row_mask:0xf bank_mask:0xf
	v_mov_b32_dpp v150, v82 row_ror:2 row_mask:0xf bank_mask:0xf
	v_mov_b32_dpp v155, v83 row_ror:1 row_mask:0xf bank_mask:0xf
	v_mov_b32_dpp v154, v83 row_ror:2 row_mask:0xf bank_mask:0xf
	v_mov_b32_dpp v128, v80 row_ror:1 row_mask:0xf bank_mask:0xf
	v_mov_b32_dpp v126, v80 row_ror:2 row_mask:0xf bank_mask:0xf
	v_mov_b32_dpp v134, v81 row_ror:1 row_mask:0xf bank_mask:0xf
	v_mov_b32_dpp v132, v81 row_ror:2 row_mask:0xf bank_mask:0xf
	v_lshl_add_u64 v[42:43], s[96:97], 0, v[54:55]
	v_lshl_add_u64 v[44:45], s[62:63], 0, v[54:55]
	global_load_dwordx4 v[50:53], v[42:43], off
	global_load_dwordx4 v[46:49], v[44:45], off
	v_lshl_add_u64 v[42:43], s[64:65], 0, v[54:55]
	v_lshl_add_u64 v[54:55], s[66:67], 0, v[54:55]
	global_load_dwordx4 v[42:45], v[42:43], off
	s_nop 1
	global_load_dwordx4 v[54:57], v[54:55], off
	s_nop 1
	v_mov_b32_dpp v104, v88 row_ror:1 row_mask:0xf bank_mask:0xf
	v_mov_b32_dpp v108, v88 row_ror:2 row_mask:0xf bank_mask:0xf
	v_mov_b32_dpp v105, v89 row_ror:1 row_mask:0xf bank_mask:0xf
	v_mov_b32_dpp v109, v89 row_ror:2 row_mask:0xf bank_mask:0xf
	v_mov_b32_dpp v106, v86 row_ror:1 row_mask:0xf bank_mask:0xf
	v_mov_b32_dpp v110, v86 row_ror:2 row_mask:0xf bank_mask:0xf
	v_mov_b32_dpp v107, v87 row_ror:1 row_mask:0xf bank_mask:0xf
	v_mov_b32_dpp v111, v87 row_ror:2 row_mask:0xf bank_mask:0xf
	s_and_saveexec_b64 s[0:1], vcc
	s_cbranch_execz .Lcg_skip2
	s_waitcnt vmcnt(4)
	v_pk_fma_f32 v[156:157], v[60:61], v[114:115], v[72:73]
	s_nop 0
	v_pk_fma_f32 v[156:157], v[64:65], v[116:117], v[156:157]
	s_nop 0
	v_pk_fma_f32 v[92:93], v[92:93], v[68:69], v[156:157]
	v_pk_fma_f32 v[156:157], v[58:59], v[118:119], v[70:71]
	v_pk_fma_f32 v[156:157], v[62:63], v[120:121], v[156:157]
	v_pk_fma_f32 v[90:91], v[90:91], v[66:67], v[156:157]
	v_pk_mul_f32 v[156:157], v[90:91], s[98:99] op_sel_hi:[1,0]
	v_pk_mul_f32 v[158:159], v[92:93], s[98:99] op_sel_hi:[1,0]
	v_exp_f32_e32 v156, v156
	v_exp_f32_e32 v157, v157
	v_exp_f32_e32 v158, v158
	v_exp_f32_e32 v159, v159
	v_pk_add_f32 v[156:157], v[156:157], 1.0 op_sel_hi:[1,0]
	v_pk_add_f32 v[158:159], v[158:159], 1.0 op_sel_hi:[1,0]
	v_rcp_f32_e32 v156, v156
	v_rcp_f32_e32 v157, v157
	v_rcp_f32_e32 v158, v158
	v_rcp_f32_e32 v159, v159
	v_pk_mul_f32 v[90:91], v[90:91], v[156:157]
	v_pk_mul_f32 v[92:93], v[92:93], v[158:159]
	s_waitcnt vmcnt(0)
	v_pk_fma_f32 v[156:157], v[52:53], v[110:111], v[56:57]
	v_pk_fma_f32 v[158:159], v[50:51], v[108:109], v[54:55]
	v_pk_fma_f32 v[156:157], v[48:49], v[106:107], v[156:157]
	v_pk_fma_f32 v[158:159], v[46:47], v[104:105], v[158:159]
	v_pk_fma_f32 v[86:87], v[86:87], v[44:45], v[156:157]
	v_pk_fma_f32 v[88:89], v[88:89], v[42:43], v[158:159]
	v_pk_mul_f32 v[86:87], v[92:93], v[86:87]
	v_pk_mul_f32 v[88:89], v[90:91], v[88:89]
	s_nop 0
	v_cvt_pk_bf16_f32 v88, v88, v89
	v_cvt_pk_bf16_f32 v89, v86, v87
	v_mov_b64_e32 v[86:87], s[36:37]
	v_mad_i64_i32 v[86:87], s[6:7], v74, s46, v[86:87]
	v_lshl_add_u64 v[86:87], v[94:95], 1, v[86:87]
	global_store_dwordx2 v[86:87], v[88:89], off
.LBB0_127:
	s_or_b64 exec, exec, s[0:1]
	v_cmp_eq_u32_e64 s[42:43], 0, v97
	v_cndmask_b32_e32 v89, v119, v152, vcc
	v_cndmask_b32_e32 v88, v118, v136, vcc
	v_cndmask_b32_e64 v87, v153, v121, s[42:43]
	v_cndmask_b32_e64 v86, v137, v120, s[42:43]
	s_waitcnt vmcnt(4)
	v_pk_fma_f32 v[88:89], v[58:59], v[88:89], v[70:71]
	v_cndmask_b32_e32 v93, v115, v129, vcc
	v_cndmask_b32_e32 v92, v114, v124, vcc
	v_pk_fma_f32 v[86:87], v[62:63], v[86:87], v[88:89]
	v_cndmask_b32_e64 v91, v131, v117, s[42:43]
	v_cndmask_b32_e64 v90, v125, v116, s[42:43]
	v_pk_fma_f32 v[92:93], v[60:61], v[92:93], v[72:73]
	v_pk_fma_f32 v[86:87], v[100:101], v[66:67], v[86:87]
	v_pk_fma_f32 v[90:91], v[64:65], v[90:91], v[92:93]
	v_cndmask_b32_e32 v101, v152, v133, vcc
	v_cndmask_b32_e32 v100, v136, v127, vcc
	v_pk_fma_f32 v[90:91], v[98:99], v[68:69], v[90:91]
	v_cndmask_b32_e64 v99, v135, v153, s[42:43]
	v_cndmask_b32_e64 v98, v130, v137, s[42:43]
	v_pk_fma_f32 v[100:101], v[58:59], v[100:101], v[70:71]
	v_cndmask_b32_e32 v115, v129, v122, vcc
	v_pk_fma_f32 v[98:99], v[62:63], v[98:99], v[100:101]
	v_cndmask_b32_e32 v114, v124, v0, vcc
	v_pk_fma_f32 v[98:99], v[112:113], v[66:67], v[98:99]
	v_cndmask_b32_e64 v113, v123, v131, s[42:43]
	v_cndmask_b32_e64 v112, v75, v125, s[42:43]
	v_pk_fma_f32 v[114:115], v[60:61], v[114:115], v[72:73]
	v_cndmask_b32_e32 v117, v133, v154, vcc
	v_cndmask_b32_e32 v116, v127, v150, vcc
	v_pk_fma_f32 v[112:113], v[64:65], v[112:113], v[114:115]
	v_cndmask_b32_e64 v115, v155, v135, s[42:43]
	v_cndmask_b32_e64 v114, v151, v130, s[42:43]
	v_pk_fma_f32 v[58:59], v[58:59], v[116:117], v[70:71]
	v_cndmask_b32_e32 v71, v122, v132, vcc
	v_pk_fma_f32 v[58:59], v[62:63], v[114:115], v[58:59]
	v_cndmask_b32_e32 v70, v0, v126, vcc
	v_pk_fma_f32 v[58:59], v[82:83], v[66:67], v[58:59]
	v_cndmask_b32_e64 v67, v134, v123, s[42:43]
	v_cndmask_b32_e64 v66, v128, v75, s[42:43]
	v_pk_fma_f32 v[60:61], v[60:61], v[70:71], v[72:73]
	v_pk_fma_f32 v[60:61], v[64:65], v[66:67], v[60:61]
	v_mov_b32_e32 v85, v84
	v_pk_fma_f32 v[60:61], v[80:81], v[68:69], v[60:61]
	v_mov_b32_e32 v97, v96
	v_mov_b32_e32 v66, v84
	v_mov_b32_e32 v67, v84
	v_pk_mul_f32 v[40:41], v[40:41], v[66:67]
	v_pk_mul_f32 v[38:39], v[38:39], v[84:85]
	v_pk_mul_f32 v[34:35], v[34:35], v[96:97]
	s_nop 1
	v_mov_b32_e32 v66, v96
	v_mov_b32_e32 v67, v96
	s_nop 1
	v_mov_b32_dpp v85, v38 row_ror:2 row_mask:0xf bank_mask:0xf
	s_nop 1
	v_mov_b32_dpp v97, v39 row_ror:2 row_mask:0xf bank_mask:0xf
	s_nop 1
	v_mov_b32_dpp v115, v40 row_ror:2 row_mask:0xf bank_mask:0xf
	s_nop 1
	v_mov_b32_dpp v117, v41 row_ror:2 row_mask:0xf bank_mask:0xf
	v_pk_fma_f32 v[102:103], v[102:103], v[68:69], v[112:113]
	v_pk_mul_f32 v[36:37], v[36:37], v[66:67]
	v_mov_b32_dpp v84, v38 row_ror:1 row_mask:0xf bank_mask:0xf
	v_mov_b32_dpp v96, v39 row_ror:1 row_mask:0xf bank_mask:0xf
	v_mov_b32_dpp v114, v40 row_ror:1 row_mask:0xf bank_mask:0xf
	v_mov_b32_dpp v116, v41 row_ror:1 row_mask:0xf bank_mask:0xf
	v_cndmask_b32_e32 v66, v108, v85, vcc
	v_cndmask_b32_e32 v67, v109, v97, vcc
	v_cndmask_b32_e32 v68, v110, v115, vcc
	v_cndmask_b32_e32 v69, v111, v117, vcc
	v_cndmask_b32_e64 v70, v84, v104, s[42:43]
	v_cndmask_b32_e64 v71, v96, v105, s[42:43]
	v_cndmask_b32_e64 v72, v114, v106, s[42:43]
	v_cndmask_b32_e64 v73, v116, v107, s[42:43]
	s_waitcnt vmcnt(1)
	v_pk_fma_f32 v[68:69], v[52:53], v[68:69], v[56:57]
	v_pk_fma_f32 v[66:67], v[50:51], v[66:67], v[54:55]
	v_pk_fma_f32 v[68:69], v[48:49], v[72:73], v[68:69]
	v_pk_fma_f32 v[66:67], v[46:47], v[70:71], v[66:67]
	v_or_b32_e32 v0, 16, v74
	v_or_b32_e32 v82, 32, v74
	v_or_b32_e32 v83, 48, v74
	v_pk_mul_f32 v[88:89], v[86:87], s[98:99] op_sel_hi:[1,0]
	v_pk_mul_f32 v[92:93], v[90:91], s[98:99] op_sel_hi:[1,0]
	v_exp_f32_e32 v88, v88
	v_exp_f32_e32 v89, v89
	v_exp_f32_e32 v92, v92
	v_exp_f32_e32 v93, v93
	v_pk_add_f32 v[88:89], v[88:89], 1.0 op_sel_hi:[1,0]
	v_pk_add_f32 v[92:93], v[92:93], 1.0 op_sel_hi:[1,0]
	v_rcp_f32_e32 v88, v88
	v_rcp_f32_e32 v89, v89
	v_rcp_f32_e32 v92, v92
	v_rcp_f32_e32 v93, v93
	v_pk_mul_f32 v[74:75], v[86:87], v[88:89]
	v_pk_mul_f32 v[80:81], v[90:91], v[92:93]
	v_pk_fma_f32 v[40:41], v[40:41], v[44:45], v[68:69]
	v_pk_fma_f32 v[38:39], v[38:39], v[42:43], v[66:67]
	v_pk_mul_f32 v[40:41], v[80:81], v[40:41]
	v_pk_mul_f32 v[38:39], v[74:75], v[38:39]
	v_cvt_pk_bf16_f32 v38, v38, v39
	v_cvt_pk_bf16_f32 v39, v40, v41
	v_mov_b64_e32 v[40:41], s[36:37]
	v_mad_i64_i32 v[66:67], s[0:1], v0, s46, v[40:41]
	v_lshlrev_b64 v[68:69], 1, v[94:95]
	s_nop 1
	v_lshl_add_u64 v[66:67], v[66:67], 0, v[68:69]
	s_nop 1
	v_mov_b32_dpp v86, v34 row_ror:2 row_mask:0xf bank_mask:0xf
	s_nop 1
	v_mov_b32_dpp v88, v35 row_ror:2 row_mask:0xf bank_mask:0xf
	s_nop 1
	v_mov_b32_dpp v90, v36 row_ror:2 row_mask:0xf bank_mask:0xf
	s_nop 1
	v_mov_b32_dpp v92, v37 row_ror:2 row_mask:0xf bank_mask:0xf
	global_store_dwordx2 v[66:67], v[38:39], off
	v_mov_b32_dpp v0, v34 row_ror:1 row_mask:0xf bank_mask:0xf
	v_mov_b32_dpp v87, v35 row_ror:1 row_mask:0xf bank_mask:0xf
	v_mov_b32_dpp v89, v36 row_ror:1 row_mask:0xf bank_mask:0xf
	v_mov_b32_dpp v91, v37 row_ror:1 row_mask:0xf bank_mask:0xf
	v_cndmask_b32_e32 v38, v85, v86, vcc
	v_cndmask_b32_e32 v39, v97, v88, vcc
	v_cndmask_b32_e32 v66, v115, v90, vcc
	v_cndmask_b32_e32 v67, v117, v92, vcc
	v_cndmask_b32_e64 v70, v0, v84, s[42:43]
	v_cndmask_b32_e64 v71, v87, v96, s[42:43]
	v_cndmask_b32_e64 v72, v89, v114, s[42:43]
	v_cndmask_b32_e64 v73, v91, v116, s[42:43]
	v_pk_fma_f32 v[66:67], v[52:53], v[66:67], v[56:57]
	v_pk_fma_f32 v[38:39], v[50:51], v[38:39], v[54:55]
	v_pk_fma_f32 v[66:67], v[48:49], v[72:73], v[66:67]
	v_pk_fma_f32 v[38:39], v[46:47], v[70:71], v[38:39]
	v_pk_mul_f32 v[100:101], v[98:99], s[98:99] op_sel_hi:[1,0]
	v_pk_mul_f32 v[112:113], v[102:103], s[98:99] op_sel_hi:[1,0]
	v_exp_f32_e32 v100, v100
	v_exp_f32_e32 v101, v101
	v_exp_f32_e32 v112, v112
	v_exp_f32_e32 v113, v113
	v_pk_add_f32 v[100:101], v[100:101], 1.0 op_sel_hi:[1,0]
	v_pk_add_f32 v[112:113], v[112:113], 1.0 op_sel_hi:[1,0]
	v_rcp_f32_e32 v100, v100
	v_rcp_f32_e32 v101, v101
	v_rcp_f32_e32 v112, v112
	v_rcp_f32_e32 v113, v113
	v_pk_mul_f32 v[74:75], v[98:99], v[100:101]
	v_pk_mul_f32 v[80:81], v[102:103], v[112:113]
	v_pk_fma_f32 v[36:37], v[36:37], v[44:45], v[66:67]
	v_pk_fma_f32 v[34:35], v[34:35], v[42:43], v[38:39]
	v_pk_mul_f32 v[36:37], v[80:81], v[36:37]
	v_pk_mul_f32 v[34:35], v[74:75], v[34:35]
	v_cvt_pk_bf16_f32 v34, v34, v35
	v_cvt_pk_bf16_f32 v35, v36, v37
	v_mad_i64_i32 v[36:37], s[0:1], v82, s46, v[40:41]
	v_lshl_add_u64 v[36:37], v[36:37], 0, v[68:69]
	global_store_dwordx2 v[36:37], v[34:35], off
	s_nop 1
	s_nop 1
	v_mov_b32_dpp v34, v78 row_ror:2 row_mask:0xf bank_mask:0xf
	s_nop 1
	v_mov_b32_dpp v35, v79 row_ror:2 row_mask:0xf bank_mask:0xf
	s_nop 1
	v_mov_b32_dpp v36, v76 row_ror:2 row_mask:0xf bank_mask:0xf
	s_nop 1
	v_mov_b32_dpp v37, v77 row_ror:2 row_mask:0xf bank_mask:0xf
	v_mov_b32_dpp v38, v78 row_ror:1 row_mask:0xf bank_mask:0xf
	v_mov_b32_dpp v39, v79 row_ror:1 row_mask:0xf bank_mask:0xf
	v_mov_b32_dpp v66, v76 row_ror:1 row_mask:0xf bank_mask:0xf
	v_mov_b32_dpp v67, v77 row_ror:1 row_mask:0xf bank_mask:0xf
	v_cndmask_b32_e32 v34, v86, v34, vcc
	v_cndmask_b32_e32 v35, v88, v35, vcc
	v_cndmask_b32_e32 v36, v90, v36, vcc
	v_cndmask_b32_e32 v37, v92, v37, vcc
	v_cndmask_b32_e64 v38, v38, v0, s[42:43]
	v_cndmask_b32_e64 v39, v39, v87, s[42:43]
	v_cndmask_b32_e64 v66, v66, v89, s[42:43]
	v_cndmask_b32_e64 v67, v67, v91, s[42:43]
	v_pk_fma_f32 v[34:35], v[50:51], v[34:35], v[54:55]
	v_pk_fma_f32 v[36:37], v[52:53], v[36:37], v[56:57]
	v_pk_fma_f32 v[34:35], v[46:47], v[38:39], v[34:35]
	v_pk_fma_f32 v[36:37], v[48:49], v[66:67], v[36:37]
	v_pk_mul_f32 v[62:63], v[58:59], s[98:99] op_sel_hi:[1,0]
	v_pk_mul_f32 v[64:65], v[60:61], s[98:99] op_sel_hi:[1,0]
	v_exp_f32_e32 v62, v62
	v_exp_f32_e32 v63, v63
	v_exp_f32_e32 v64, v64
	v_exp_f32_e32 v65, v65
	v_pk_add_f32 v[62:63], v[62:63], 1.0 op_sel_hi:[1,0]
	v_pk_add_f32 v[64:65], v[64:65], 1.0 op_sel_hi:[1,0]
	v_rcp_f32_e32 v62, v62
	v_rcp_f32_e32 v63, v63
	v_rcp_f32_e32 v64, v64
	v_rcp_f32_e32 v65, v65
	v_pk_mul_f32 v[58:59], v[58:59], v[62:63]
	v_pk_mul_f32 v[60:61], v[60:61], v[64:65]
	v_pk_fma_f32 v[34:35], v[78:79], v[42:43], v[34:35]
	v_pk_fma_f32 v[36:37], v[76:77], v[44:45], v[36:37]
	v_pk_mul_f32 v[34:35], v[58:59], v[34:35]
	v_pk_mul_f32 v[36:37], v[60:61], v[36:37]
	v_cvt_pk_bf16_f32 v34, v34, v35
	s_nop 0
	v_cvt_pk_bf16_f32 v35, v36, v37
	v_mad_i64_i32 v[36:37], s[0:1], v83, s46, v[40:41]
	v_lshl_add_u64 v[36:37], v[36:37], 0, v[68:69]
	global_store_dwordx2 v[36:37], v[34:35], off
	s_nop 0
	v_and_b32_e32 v108, 15, v226
	v_or_b32_e32 v56, s4, v108
	v_ashrrev_i32_e32 v57, 31, v56
	v_lshl_add_u64 v[40:41], v[56:57], 3, s[38:39]
	global_load_dwordx2 v[42:43], v[40:41], off offset:1024
	global_load_dwordx2 v[38:39], v[40:41], off offset:1152
	global_load_dwordx2 v[36:37], v[40:41], off offset:1280
	s_nop 0
	global_load_dwordx2 v[40:41], v[40:41], off offset:1408
	v_ashrrev_i32_e32 v0, 1, v226
	v_and_b32_e32 v0, -8, v0
	v_add_u32_e32 v34, s21, v0
	s_waitcnt vmcnt(3)
	v_ffbh_u32_e32 v0, v43
	v_min_u32_e32 v0, 32, v0
	v_lshlrev_b64 v[42:43], v0, v[42:43]
	v_min_u32_e32 v35, 1, v42
	v_or_b32_e32 v35, v43, v35
	v_cvt_f32_u32_e32 v35, v35
	v_sub_u32_e32 v0, 32, v0
	v_ldexp_f32 v0, v35, v0
	v_fmamk_f32 v0, v0, 0x2e800000, v210
	s_nop 0
	v_rsq_f32_e32 v0, v0
	s_nop 0
	s_nop 0
	v_ashrrev_i32_e32 v35, 31, v34
	v_pk_mul_f32 v[84:85], v[32:33], v[0:1] op_sel_hi:[1,0]
	v_pk_mul_f32 v[44:45], v[30:31], v[0:1] op_sel_hi:[1,0]
	v_pk_mul_f32 v[72:73], v[28:29], v[0:1] op_sel_hi:[1,0]
	v_pk_mul_f32 v[42:43], v[26:27], v[0:1] op_sel_hi:[1,0]
	v_lshl_add_u64 v[26:27], v[34:35], 1, s[78:79]
	v_cmp_gt_u32_e32 vcc, 2, v108
	s_and_saveexec_b64 s[0:1], vcc
	s_cbranch_execz .LBB0_129
	v_mul_u32_u24_e32 v0, 0x1600, v108
	v_lshlrev_b32_e32 v0, 1, v0
	v_cvt_pk_bf16_f32 v28, v44, v45
	v_cvt_pk_bf16_f32 v29, v84, v85
	v_lshl_add_u64 v[32:33], v[26:27], 0, v[0:1]
	v_cvt_pk_bf16_f32 v30, v42, v43
	v_cvt_pk_bf16_f32 v31, v72, v73
	global_store_dwordx2 v[32:33], v[28:29], off offset:8
	global_store_dwordx2 v[32:33], v[30:31], off offset:264
.LBB0_129:
	s_or_b64 exec, exec, s[0:1]
	s_waitcnt vmcnt(0)
	v_ffbh_u32_e32 v0, v41
	v_min_u32_e32 v0, 32, v0
	v_lshlrev_b64 v[28:29], v0, v[40:41]
	v_min_u32_e32 v28, 1, v28
	v_or_b32_e32 v28, v29, v28
	v_cvt_f32_u32_e32 v28, v28
	v_sub_u32_e32 v0, 32, v0
	v_ldexp_f32 v0, v28, v0
	v_fmamk_f32 v0, v0, 0x2e800000, v210
	s_nop 1
	v_rsq_f32_e32 v0, v0
	s_nop 0
	s_nop 0
	v_pk_mul_f32 v[68:69], v[24:25], v[0:1] op_sel_hi:[1,0]
	v_pk_mul_f32 v[64:65], v[22:23], v[0:1] op_sel_hi:[1,0]
	v_pk_mul_f32 v[48:49], v[16:17], v[0:1] op_sel_hi:[1,0]
	v_pk_mul_f32 v[50:51], v[14:15], v[0:1] op_sel_hi:[1,0]
	v_cmp_lt_u32_e32 vcc, 13, v108
	s_and_saveexec_b64 s[0:1], vcc
	s_cbranch_execz .LBB0_131
	v_add_u32_e32 v0, -12, v108
	s_movk_i32 s4, 0x2c00
	v_cvt_pk_bf16_f32 v14, v64, v65
	v_cvt_pk_bf16_f32 v15, v68, v69
	v_mad_u64_u32 v[22:23], s[6:7], v0, s4, v[26:27]
	v_cvt_pk_bf16_f32 v16, v50, v51
	v_cvt_pk_bf16_f32 v17, v48, v49
	global_store_dwordx2 v[22:23], v[14:15], off offset:8
	global_store_dwordx2 v[22:23], v[16:17], off offset:264
.LBB0_131:
	s_or_b64 exec, exec, s[0:1]
	v_ffbh_u32_e32 v0, v39
	v_min_u32_e32 v0, 32, v0
	v_lshlrev_b64 v[14:15], v0, v[38:39]
	v_min_u32_e32 v14, 1, v14
	v_or_b32_e32 v14, v15, v14
	v_cvt_f32_u32_e32 v14, v14
	v_sub_u32_e32 v0, 32, v0
	v_add_u32_e32 v58, s5, v34
	v_ldexp_f32 v0, v14, v0
	v_fmamk_f32 v0, v0, 0x2e800000, v210
	s_nop 0
	v_rsq_f32_e32 v0, v0
	s_nop 0
	s_nop 0
	v_mov_b32_e32 v52, v0
	v_ffbh_u32_e32 v0, v37
	v_min_u32_e32 v0, 32, v0
	v_lshlrev_b64 v[14:15], v0, v[36:37]
	v_min_u32_e32 v14, 1, v14
	v_or_b32_e32 v14, v15, v14
	v_cvt_f32_u32_e32 v14, v14
	v_sub_u32_e32 v0, 32, v0
	v_pk_mul_f32 v[60:61], v[20:21], v[52:53] op_sel_hi:[1,0]
	v_pk_mul_f32 v[54:55], v[18:19], v[52:53] op_sel_hi:[1,0]
	v_ldexp_f32 v0, v14, v0
	v_fmamk_f32 v0, v0, 0x2e800000, v210
	s_nop 0
	v_rsq_f32_e32 v0, v0
	s_nop 0
	s_nop 0
	v_mov_b32_e32 v62, v0
	v_pk_mul_f32 v[88:89], v[12:13], v[62:63] op_sel_hi:[1,0]
	v_pk_mul_f32 v[82:83], v[10:11], v[62:63] op_sel_hi:[1,0]
	v_ashrrev_i32_e32 v59, 31, v58
	v_lshlrev_b64 v[22:23], 2, v[58:59]
	v_lshl_add_u64 v[10:11], s[44:45], 0, v[22:23]
	v_lshl_add_u64 v[12:13], s[60:61], 0, v[22:23]
	global_load_dwordx4 v[26:29], v[10:11], off
	global_load_dwordx4 v[30:33], v[12:13], off
	v_lshl_add_u64 v[10:11], s[2:3], 0, v[22:23]
	global_load_dwordx4 v[34:37], v[10:11], off
	v_lshl_add_u64 v[10:11], s[48:49], 0, v[22:23]
	global_load_dwordx4 v[38:41], v[10:11], off
	s_nop 1
	v_cmp_lt_u32_e32 vcc, 1, v108
	v_mov_b32_dpp v66, v44 row_ror:1 row_mask:0xf bank_mask:0xf
	v_mov_b32_dpp v87, v44 row_ror:2 row_mask:0xf bank_mask:0xf
	v_mov_b32_dpp v67, v45 row_ror:1 row_mask:0xf bank_mask:0xf
	v_mov_b32_dpp v86, v45 row_ror:2 row_mask:0xf bank_mask:0xf
	v_mov_b32_dpp v80, v84 row_ror:1 row_mask:0xf bank_mask:0xf
	v_mov_b32_dpp v91, v84 row_ror:2 row_mask:0xf bank_mask:0xf
	v_mov_b32_dpp v81, v85 row_ror:1 row_mask:0xf bank_mask:0xf
	v_mov_b32_dpp v90, v85 row_ror:2 row_mask:0xf bank_mask:0xf
	v_mov_b32_dpp v0, v54 row_ror:1 row_mask:0xf bank_mask:0xf
	v_mov_b32_dpp v97, v54 row_ror:2 row_mask:0xf bank_mask:0xf
	v_mov_b32_dpp v109, v55 row_ror:1 row_mask:0xf bank_mask:0xf
	v_mov_b32_dpp v96, v55 row_ror:2 row_mask:0xf bank_mask:0xf
	v_mov_b32_dpp v110, v60 row_ror:1 row_mask:0xf bank_mask:0xf
	v_mov_b32_dpp v99, v60 row_ror:2 row_mask:0xf bank_mask:0xf
	v_mov_b32_dpp v111, v61 row_ror:1 row_mask:0xf bank_mask:0xf
	v_mov_b32_dpp v98, v61 row_ror:2 row_mask:0xf bank_mask:0xf
	v_mov_b32_dpp v112, v82 row_ror:1 row_mask:0xf bank_mask:0xf
	v_mov_b32_dpp v93, v82 row_ror:2 row_mask:0xf bank_mask:0xf
	v_mov_b32_dpp v113, v83 row_ror:1 row_mask:0xf bank_mask:0xf
	v_mov_b32_dpp v92, v83 row_ror:2 row_mask:0xf bank_mask:0xf
	v_mov_b32_dpp v114, v88 row_ror:1 row_mask:0xf bank_mask:0xf
	v_mov_b32_dpp v95, v88 row_ror:2 row_mask:0xf bank_mask:0xf
	v_mov_b32_dpp v115, v89 row_ror:1 row_mask:0xf bank_mask:0xf
	v_mov_b32_dpp v94, v89 row_ror:2 row_mask:0xf bank_mask:0xf
	v_mov_b32_dpp v57, v64 row_ror:1 row_mask:0xf bank_mask:0xf
	v_mov_b32_dpp v101, v64 row_ror:2 row_mask:0xf bank_mask:0xf
	v_mov_b32_dpp v116, v65 row_ror:1 row_mask:0xf bank_mask:0xf
	v_mov_b32_dpp v100, v65 row_ror:2 row_mask:0xf bank_mask:0xf
	v_mov_b32_dpp v117, v68 row_ror:1 row_mask:0xf bank_mask:0xf
	v_mov_b32_dpp v103, v68 row_ror:2 row_mask:0xf bank_mask:0xf
	v_mov_b32_dpp v118, v69 row_ror:1 row_mask:0xf bank_mask:0xf
	v_mov_b32_dpp v102, v69 row_ror:2 row_mask:0xf bank_mask:0xf
	v_cmp_gt_u32_e64 s[42:43], 2, v108
	v_lshl_add_u64 v[10:11], s[96:97], 0, v[22:23]
	v_lshl_add_u64 v[12:13], s[62:63], 0, v[22:23]
	global_load_dwordx4 v[18:21], v[10:11], off
	global_load_dwordx4 v[14:17], v[12:13], off
	v_lshl_add_u64 v[10:11], s[64:65], 0, v[22:23]
	v_lshl_add_u64 v[22:23], s[66:67], 0, v[22:23]
	global_load_dwordx4 v[10:13], v[10:11], off
	s_nop 1
	global_load_dwordx4 v[22:25], v[22:23], off
	s_nop 1
	v_mov_b32_dpp v70, v42 row_ror:1 row_mask:0xf bank_mask:0xf
	v_mov_b32_dpp v76, v42 row_ror:2 row_mask:0xf bank_mask:0xf
	v_mov_b32_dpp v71, v43 row_ror:1 row_mask:0xf bank_mask:0xf
	v_mov_b32_dpp v77, v43 row_ror:2 row_mask:0xf bank_mask:0xf
	v_mov_b32_dpp v74, v72 row_ror:1 row_mask:0xf bank_mask:0xf
	v_mov_b32_dpp v78, v72 row_ror:2 row_mask:0xf bank_mask:0xf
	v_mov_b32_dpp v75, v73 row_ror:1 row_mask:0xf bank_mask:0xf
	v_mov_b32_dpp v79, v73 row_ror:2 row_mask:0xf bank_mask:0xf
	s_and_saveexec_b64 s[0:1], s[42:43]
	s_xor_b64 s[0:1], exec, s[0:1]
	s_or_saveexec_b64 s[0:1], s[0:1]
	v_mov_b64_e32 v[106:107], v[98:99]
	v_mov_b64_e32 v[104:105], v[96:97]
	s_xor_b64 exec, exec, s[0:1]
	s_cbranch_execz .Lcg_skip3
	s_waitcnt vmcnt(4)
	v_pk_fma_f32 v[46:47], v[28:29], v[90:91], v[40:41] op_sel:[0,1,0] op_sel_hi:[1,0,1]
	v_mov_b64_e32 v[106:107], v[94:95]
	v_pk_fma_f32 v[46:47], v[32:33], v[80:81], v[46:47]
	v_mov_b64_e32 v[104:105], v[92:93]
	v_pk_fma_f32 v[46:47], v[84:85], v[36:37], v[46:47]
	v_pk_fma_f32 v[84:85], v[26:27], v[86:87], v[38:39] op_sel:[0,1,0] op_sel_hi:[1,0,1]
	v_pk_fma_f32 v[84:85], v[30:31], v[66:67], v[84:85]
	v_pk_fma_f32 v[44:45], v[44:45], v[34:35], v[84:85]
	v_pk_mul_f32 v[86:87], v[46:47], s[98:99] op_sel_hi:[1,0]
	v_exp_f32_e32 v86, v86
	v_exp_f32_e32 v87, v87
	s_nop 0
	v_pk_add_f32 v[86:87], v[86:87], 1.0 op_sel_hi:[1,0]
	v_rcp_f32_e32 v86, v86
	v_rcp_f32_e32 v87, v87
	s_nop 0
	v_pk_mul_f32 v[46:47], v[46:47], v[86:87]
	s_waitcnt vmcnt(0)
	v_pk_fma_f32 v[86:87], v[18:19], v[76:77], v[22:23]
	v_add_u32_e32 v53, 0x80, v56
	v_pk_fma_f32 v[86:87], v[14:15], v[70:71], v[86:87]
	v_pk_mul_f32 v[84:85], v[44:45], s[98:99] op_sel_hi:[1,0]
	v_exp_f32_e32 v84, v84
	v_exp_f32_e32 v85, v85
	s_nop 0
	v_pk_add_f32 v[84:85], v[84:85], 1.0 op_sel_hi:[1,0]
	v_rcp_f32_e32 v84, v84
	v_rcp_f32_e32 v85, v85
	s_nop 0
	v_pk_mul_f32 v[44:45], v[44:45], v[84:85]
	v_pk_fma_f32 v[42:43], v[42:43], v[10:11], v[86:87]
	v_pk_fma_f32 v[84:85], v[20:21], v[78:79], v[24:25]
	v_pk_mul_f32 v[42:43], v[44:45], v[42:43]
	v_mov_b64_e32 v[44:45], s[36:37]
	v_pk_fma_f32 v[84:85], v[16:17], v[74:75], v[84:85]
	v_mad_i64_i32 v[44:45], s[4:5], v53, s46, v[44:45]
	v_pk_fma_f32 v[72:73], v[72:73], v[12:13], v[84:85]
	v_lshl_add_u64 v[44:45], v[58:59], 1, v[44:45]
	v_mov_b64_e32 v[90:91], v[98:99]
	v_mov_b64_e32 v[86:87], v[96:97]
	v_mov_b64_e32 v[94:95], v[102:103]
	v_mov_b64_e32 v[92:93], v[100:101]
	v_pk_mul_f32 v[46:47], v[46:47], v[72:73]
	v_cvt_pk_bf16_f32 v42, v42, v43
	s_nop 0
	v_cvt_pk_bf16_f32 v43, v46, v47
	global_store_dwordx2 v[44:45], v[42:43], off

.LBB0_701:
	v_lshl_add_u32 v142, s54, 8, v174
	v_ashrrev_i32_e32 v143, 31, v142
	v_lshl_add_u64 v[140:141], v[142:143], 3, s[2:3]
	global_load_dwordx2 v[158:159], v[140:141], off
	global_load_dwordx2 v[156:157], v[140:141], off offset:128
	global_load_dwordx2 v[154:155], v[140:141], off offset:256
	global_load_dwordx2 v[152:153], v[140:141], off offset:384
	global_load_dwordx2 v[150:151], v[140:141], off offset:1024
	global_load_dwordx2 v[148:149], v[140:141], off offset:1152
	global_load_dwordx2 v[146:147], v[140:141], off offset:1280
	global_load_dwordx2 v[144:145], v[140:141], off offset:1408
	s_cmp_gt_i32 s42, 13
	s_cselect_b64 s[0:1], -1, 0
	s_cmp_lt_i32 s42, 14
	s_cselect_b64 s[6:7], -1, 0
	s_and_b64 vcc, s[6:7], exec
	s_cselect_b32 s6, 0, -14
	s_movk_i32 s7, 0xe00
	s_mov_b32 s34, 0x800000
	s_cselect_b32 s25, s18, s31
	s_cselect_b32 s28, s17, s30
	s_cselect_b32 s24, s7, 0xc00
	s_add_i32 s6, s6, s42
	v_lshl_or_b32 v140, s6, 8, v176
	v_ashrrev_i32_e32 v141, 31, v140
	s_mov_b64 s[6:7], -1
	s_waitcnt vmcnt(0)
	v_ffbh_u32_e32 v143, v159
	v_min_u32_e32 v143, 32, v143
	v_lshlrev_b64 v[158:159], v143, v[158:159]
	v_min_u32_e32 v158, 1, v158
	v_or_b32_e32 v158, v159, v158
	v_cvt_f32_u32_e32 v158, v158
	v_sub_u32_e32 v143, 32, v143
	v_ldexp_f32 v143, v158, v143
	v_fmamk_f32 v143, v143, 0x2e800000, v210
	s_nop 0
	v_rsq_f32_e32 v143, v143
	s_nop 0
	s_nop 0
	v_mov_b32_e32 v158, v143
	v_pk_mul_f32 v[128:129], v[128:129], v[158:159] op_sel_hi:[1,0]
	v_pk_mul_f32 v[170:171], v[126:127], v[158:159] op_sel_hi:[1,0]
	v_pk_mul_f32 v[124:125], v[124:125], v[158:159] op_sel_hi:[1,0]
	v_pk_mul_f32 v[126:127], v[122:123], v[158:159] op_sel_hi:[1,0]
	s_cbranch_vccnz .LBB0_703
	s_mov_b32 s98, 0xbfb8aa3b
	s_mov_b32 s32, 0x437f0000
	v_pk_mul_f32 v[170:171], v[170:171], s[98:99] op_sel_hi:[1,0]
	v_pk_mul_f32 v[128:129], v[128:129], s[98:99] op_sel_hi:[1,0]
	v_pk_mul_f32 v[126:127], v[126:127], s[98:99] op_sel_hi:[1,0]
	v_pk_mul_f32 v[124:125], v[124:125], s[98:99] op_sel_hi:[1,0]
	v_exp_f32_e32 v170, v170
	v_exp_f32_e32 v171, v171
	v_exp_f32_e32 v128, v128
	v_exp_f32_e32 v129, v129
	v_exp_f32_e32 v126, v126
	v_exp_f32_e32 v127, v127
	v_exp_f32_e32 v124, v124
	v_exp_f32_e32 v125, v125
	v_pk_add_f32 v[170:171], v[170:171], 1.0 op_sel_hi:[1,0]
	v_pk_add_f32 v[128:129], v[128:129], 1.0 op_sel_hi:[1,0]
	v_pk_add_f32 v[126:127], v[126:127], 1.0 op_sel_hi:[1,0]
	v_pk_add_f32 v[124:125], v[124:125], 1.0 op_sel_hi:[1,0]
	v_rcp_f32_e32 v170, v170
	v_rcp_f32_e32 v171, v171
	v_rcp_f32_e32 v128, v128
	v_rcp_f32_e32 v129, v129
	v_rcp_f32_e32 v126, v126
	v_rcp_f32_e32 v127, v127
	v_rcp_f32_e32 v124, v124
	v_rcp_f32_e32 v125, v125
	v_pk_mul_f32 v[170:171], v[170:171], s[32:33] op_sel_hi:[1,0]
	v_pk_mul_f32 v[128:129], v[128:129], s[32:33] op_sel_hi:[1,0]
	v_pk_mul_f32 v[126:127], v[126:127], s[32:33] op_sel_hi:[1,0]
	v_pk_mul_f32 v[124:125], v[124:125], s[32:33] op_sel_hi:[1,0]
	v_max_f32_e32 v170, 1.0, v170
	v_max_f32_e32 v171, 1.0, v171
	v_max_f32_e32 v128, 1.0, v128
	v_max_f32_e32 v129, 1.0, v129
	v_max_f32_e32 v126, 1.0, v126
	v_max_f32_e32 v127, 1.0, v127
	v_max_f32_e32 v124, 1.0, v124
	v_max_f32_e32 v125, 1.0, v125
	v_rndne_f32_e32 v170, v170
	v_rndne_f32_e32 v171, v171
	v_rndne_f32_e32 v128, v128
	v_rndne_f32_e32 v129, v129
	v_rndne_f32_e32 v126, v126
	v_rndne_f32_e32 v127, v127
	v_rndne_f32_e32 v124, v124
	v_rndne_f32_e32 v125, v125
	v_cvt_pk_u8_f32 v122, v170, 0, 0
	v_cvt_pk_u8_f32 v122, v171, 1, v122
	v_cvt_pk_u8_f32 v123, v126, 0, 0
	v_cvt_pk_u8_f32 v123, v127, 1, v123
	v_cvt_pk_u8_f32 v122, v128, 2, v122
	v_cvt_pk_u8_f32 v122, v129, 3, v122
	v_cvt_pk_u8_f32 v123, v124, 2, v123
	v_cvt_pk_u8_f32 v123, v125, 3, v123
	v_mov_b64_e32 v[172:173], s[30:31]
	v_mad_i64_i32 v[172:173], s[6:7], v142, s55, v[172:173]
	v_lshl_add_u64 v[172:173], v[172:173], 0, v[140:141]
	s_mov_b64 s[6:7], 0
	v_mov_b32_e32 v246, v122
	v_mov_b32_e32 v247, v123

.LBB0_709:
	v_ffbh_u32_e32 v114, v157
	v_min_u32_e32 v116, 32, v114
	v_lshlrev_b64 v[114:115], v116, v[156:157]
	v_min_u32_e32 v114, 1, v114
	v_or_b32_e32 v114, v115, v114
	v_cvt_f32_u32_e32 v114, v114
	v_sub_u32_e32 v115, 32, v116
	v_or_b32_e32 v118, 16, v142
	s_mov_b64 s[0:1], -1
	v_ldexp_f32 v114, v114, v115
	v_fmamk_f32 v114, v114, 0x2e800000, v210
	s_nop 1
	v_rsq_f32_e32 v114, v114
	s_nop 0
	s_nop 0
	v_pk_mul_f32 v[112:113], v[112:113], v[114:115] op_sel_hi:[1,0]
	v_pk_mul_f32 v[116:117], v[110:111], v[114:115] op_sel_hi:[1,0]
	v_pk_mul_f32 v[108:109], v[108:109], v[114:115] op_sel_hi:[1,0]
	v_pk_mul_f32 v[110:111], v[106:107], v[114:115] op_sel_hi:[1,0]
	s_and_b64 vcc, exec, s[42:43]
	s_cbranch_vccnz .LBB0_711
	s_mov_b32 s98, 0xbfb8aa3b
	s_mov_b32 s32, 0x437f0000
	v_pk_mul_f32 v[116:117], v[116:117], s[98:99] op_sel_hi:[1,0]
	v_pk_mul_f32 v[112:113], v[112:113], s[98:99] op_sel_hi:[1,0]
	v_pk_mul_f32 v[110:111], v[110:111], s[98:99] op_sel_hi:[1,0]
	v_pk_mul_f32 v[108:109], v[108:109], s[98:99] op_sel_hi:[1,0]
	v_exp_f32_e32 v116, v116
	v_exp_f32_e32 v117, v117
	v_exp_f32_e32 v112, v112
	v_exp_f32_e32 v113, v113
	v_exp_f32_e32 v110, v110
	v_exp_f32_e32 v111, v111
	v_exp_f32_e32 v108, v108
	v_exp_f32_e32 v109, v109
	v_pk_add_f32 v[116:117], v[116:117], 1.0 op_sel_hi:[1,0]
	v_pk_add_f32 v[112:113], v[112:113], 1.0 op_sel_hi:[1,0]
	v_pk_add_f32 v[110:111], v[110:111], 1.0 op_sel_hi:[1,0]
	v_pk_add_f32 v[108:109], v[108:109], 1.0 op_sel_hi:[1,0]
	v_rcp_f32_e32 v116, v116
	v_rcp_f32_e32 v117, v117
	v_rcp_f32_e32 v112, v112
	v_rcp_f32_e32 v113, v113
	v_rcp_f32_e32 v110, v110
	v_rcp_f32_e32 v111, v111
	v_rcp_f32_e32 v108, v108
	v_rcp_f32_e32 v109, v109
	v_pk_mul_f32 v[116:117], v[116:117], s[32:33] op_sel_hi:[1,0]
	v_pk_mul_f32 v[112:113], v[112:113], s[32:33] op_sel_hi:[1,0]
	v_pk_mul_f32 v[110:111], v[110:111], s[32:33] op_sel_hi:[1,0]
	v_pk_mul_f32 v[108:109], v[108:109], s[32:33] op_sel_hi:[1,0]
	v_max_f32_e32 v116, 1.0, v116
	v_max_f32_e32 v117, 1.0, v117
	v_max_f32_e32 v112, 1.0, v112
	v_max_f32_e32 v113, 1.0, v113
	v_max_f32_e32 v110, 1.0, v110
	v_max_f32_e32 v111, 1.0, v111
	v_max_f32_e32 v108, 1.0, v108
	v_max_f32_e32 v109, 1.0, v109
	v_rndne_f32_e32 v116, v116
	v_rndne_f32_e32 v117, v117
	v_rndne_f32_e32 v112, v112
	v_rndne_f32_e32 v113, v113
	v_rndne_f32_e32 v110, v110
	v_rndne_f32_e32 v111, v111
	v_rndne_f32_e32 v108, v108
	v_rndne_f32_e32 v109, v109
	v_cvt_pk_u8_f32 v106, v116, 0, 0
	v_cvt_pk_u8_f32 v106, v117, 1, v106
	v_cvt_pk_u8_f32 v107, v110, 0, 0
	v_cvt_pk_u8_f32 v107, v111, 1, v107
	v_cvt_pk_u8_f32 v106, v112, 2, v106
	v_cvt_pk_u8_f32 v106, v113, 3, v106
	v_cvt_pk_u8_f32 v107, v108, 2, v107
	v_cvt_pk_u8_f32 v107, v109, 3, v107
	v_mov_b64_e32 v[120:121], s[30:31]
	v_mad_i64_i32 v[120:121], s[0:1], v118, s55, v[120:121]
	v_lshl_add_u64 v[120:121], v[120:121], 0, v[140:141]
	s_mov_b64 s[0:1], 0
	v_mov_b32_e32 v246, v106
	v_mov_b32_e32 v247, v107

.LBB0_717:
	v_ffbh_u32_e32 v98, v155
	v_min_u32_e32 v100, 32, v98
	v_lshlrev_b64 v[98:99], v100, v[154:155]
	v_min_u32_e32 v98, 1, v98
	v_or_b32_e32 v98, v99, v98
	v_cvt_f32_u32_e32 v98, v98
	v_sub_u32_e32 v99, 32, v100
	v_or_b32_e32 v102, 32, v142
	s_mov_b64 s[0:1], -1
	v_ldexp_f32 v98, v98, v99
	v_fmamk_f32 v98, v98, 0x2e800000, v210
	s_nop 1
	v_rsq_f32_e32 v98, v98
	s_nop 0
	s_nop 0
	v_pk_mul_f32 v[96:97], v[96:97], v[98:99] op_sel_hi:[1,0]
	v_pk_mul_f32 v[100:101], v[94:95], v[98:99] op_sel_hi:[1,0]
	v_pk_mul_f32 v[92:93], v[92:93], v[98:99] op_sel_hi:[1,0]
	v_pk_mul_f32 v[94:95], v[90:91], v[98:99] op_sel_hi:[1,0]
	s_and_b64 vcc, exec, s[42:43]
	s_cbranch_vccnz .LBB0_719
	s_mov_b32 s98, 0xbfb8aa3b
	s_mov_b32 s32, 0x437f0000
	v_pk_mul_f32 v[100:101], v[100:101], s[98:99] op_sel_hi:[1,0]
	v_pk_mul_f32 v[96:97], v[96:97], s[98:99] op_sel_hi:[1,0]
	v_pk_mul_f32 v[94:95], v[94:95], s[98:99] op_sel_hi:[1,0]
	v_pk_mul_f32 v[92:93], v[92:93], s[98:99] op_sel_hi:[1,0]
	v_exp_f32_e32 v100, v100
	v_exp_f32_e32 v101, v101
	v_exp_f32_e32 v96, v96
	v_exp_f32_e32 v97, v97
	v_exp_f32_e32 v94, v94
	v_exp_f32_e32 v95, v95
	v_exp_f32_e32 v92, v92
	v_exp_f32_e32 v93, v93
	v_pk_add_f32 v[100:101], v[100:101], 1.0 op_sel_hi:[1,0]
	v_pk_add_f32 v[96:97], v[96:97], 1.0 op_sel_hi:[1,0]
	v_pk_add_f32 v[94:95], v[94:95], 1.0 op_sel_hi:[1,0]
	v_pk_add_f32 v[92:93], v[92:93], 1.0 op_sel_hi:[1,0]
	v_rcp_f32_e32 v100, v100
	v_rcp_f32_e32 v101, v101
	v_rcp_f32_e32 v96, v96
	v_rcp_f32_e32 v97, v97
	v_rcp_f32_e32 v94, v94
	v_rcp_f32_e32 v95, v95
	v_rcp_f32_e32 v92, v92
	v_rcp_f32_e32 v93, v93
	v_pk_mul_f32 v[100:101], v[100:101], s[32:33] op_sel_hi:[1,0]
	v_pk_mul_f32 v[96:97], v[96:97], s[32:33] op_sel_hi:[1,0]
	v_pk_mul_f32 v[94:95], v[94:95], s[32:33] op_sel_hi:[1,0]
	v_pk_mul_f32 v[92:93], v[92:93], s[32:33] op_sel_hi:[1,0]
	v_max_f32_e32 v100, 1.0, v100
	v_max_f32_e32 v101, 1.0, v101
	v_max_f32_e32 v96, 1.0, v96
	v_max_f32_e32 v97, 1.0, v97
	v_max_f32_e32 v94, 1.0, v94
	v_max_f32_e32 v95, 1.0, v95
	v_max_f32_e32 v92, 1.0, v92
	v_max_f32_e32 v93, 1.0, v93
	v_rndne_f32_e32 v100, v100
	v_rndne_f32_e32 v101, v101
	v_rndne_f32_e32 v96, v96
	v_rndne_f32_e32 v97, v97
	v_rndne_f32_e32 v94, v94
	v_rndne_f32_e32 v95, v95
	v_rndne_f32_e32 v92, v92
	v_rndne_f32_e32 v93, v93
	v_cvt_pk_u8_f32 v90, v100, 0, 0
	v_cvt_pk_u8_f32 v90, v101, 1, v90
	v_cvt_pk_u8_f32 v91, v94, 0, 0
	v_cvt_pk_u8_f32 v91, v95, 1, v91
	v_cvt_pk_u8_f32 v90, v96, 2, v90
	v_cvt_pk_u8_f32 v90, v97, 3, v90
	v_cvt_pk_u8_f32 v91, v92, 2, v91
	v_cvt_pk_u8_f32 v91, v93, 3, v91
	v_mov_b64_e32 v[104:105], s[30:31]
	v_mad_i64_i32 v[104:105], s[0:1], v102, s55, v[104:105]
	v_lshl_add_u64 v[104:105], v[104:105], 0, v[140:141]
	s_mov_b64 s[0:1], 0
	v_mov_b32_e32 v246, v90
	v_mov_b32_e32 v247, v91

.LBB0_725:
	v_ffbh_u32_e32 v82, v153
	v_min_u32_e32 v84, 32, v82
	v_lshlrev_b64 v[82:83], v84, v[152:153]
	v_min_u32_e32 v82, 1, v82
	v_or_b32_e32 v82, v83, v82
	v_cvt_f32_u32_e32 v82, v82
	v_sub_u32_e32 v83, 32, v84
	v_or_b32_e32 v86, 48, v142
	s_mov_b64 s[0:1], -1
	v_ldexp_f32 v82, v82, v83
	v_fmamk_f32 v82, v82, 0x2e800000, v210
	s_nop 1
	v_rsq_f32_e32 v82, v82
	s_nop 0
	s_nop 0
	v_pk_mul_f32 v[80:81], v[80:81], v[82:83] op_sel_hi:[1,0]
	v_pk_mul_f32 v[84:85], v[78:79], v[82:83] op_sel_hi:[1,0]
	v_pk_mul_f32 v[76:77], v[76:77], v[82:83] op_sel_hi:[1,0]
	v_pk_mul_f32 v[78:79], v[74:75], v[82:83] op_sel_hi:[1,0]
	s_and_b64 vcc, exec, s[42:43]
	s_cbranch_vccnz .LBB0_727
	s_mov_b32 s98, 0xbfb8aa3b
	s_mov_b32 s32, 0x437f0000
	v_pk_mul_f32 v[84:85], v[84:85], s[98:99] op_sel_hi:[1,0]
	v_pk_mul_f32 v[80:81], v[80:81], s[98:99] op_sel_hi:[1,0]
	v_pk_mul_f32 v[78:79], v[78:79], s[98:99] op_sel_hi:[1,0]
	v_pk_mul_f32 v[76:77], v[76:77], s[98:99] op_sel_hi:[1,0]
	v_exp_f32_e32 v84, v84
	v_exp_f32_e32 v85, v85
	v_exp_f32_e32 v80, v80
	v_exp_f32_e32 v81, v81
	v_exp_f32_e32 v78, v78
	v_exp_f32_e32 v79, v79
	v_exp_f32_e32 v76, v76
	v_exp_f32_e32 v77, v77
	v_pk_add_f32 v[84:85], v[84:85], 1.0 op_sel_hi:[1,0]
	v_pk_add_f32 v[80:81], v[80:81], 1.0 op_sel_hi:[1,0]
	v_pk_add_f32 v[78:79], v[78:79], 1.0 op_sel_hi:[1,0]
	v_pk_add_f32 v[76:77], v[76:77], 1.0 op_sel_hi:[1,0]
	v_rcp_f32_e32 v84, v84
	v_rcp_f32_e32 v85, v85
	v_rcp_f32_e32 v80, v80
	v_rcp_f32_e32 v81, v81
	v_rcp_f32_e32 v78, v78
	v_rcp_f32_e32 v79, v79
	v_rcp_f32_e32 v76, v76
	v_rcp_f32_e32 v77, v77
	v_pk_mul_f32 v[84:85], v[84:85], s[32:33] op_sel_hi:[1,0]
	v_pk_mul_f32 v[80:81], v[80:81], s[32:33] op_sel_hi:[1,0]
	v_pk_mul_f32 v[78:79], v[78:79], s[32:33] op_sel_hi:[1,0]
	v_pk_mul_f32 v[76:77], v[76:77], s[32:33] op_sel_hi:[1,0]
	v_max_f32_e32 v84, 1.0, v84
	v_max_f32_e32 v85, 1.0, v85
	v_max_f32_e32 v80, 1.0, v80
	v_max_f32_e32 v81, 1.0, v81
	v_max_f32_e32 v78, 1.0, v78
	v_max_f32_e32 v79, 1.0, v79
	v_max_f32_e32 v76, 1.0, v76
	v_max_f32_e32 v77, 1.0, v77
	v_rndne_f32_e32 v84, v84
	v_rndne_f32_e32 v85, v85
	v_rndne_f32_e32 v80, v80
	v_rndne_f32_e32 v81, v81
	v_rndne_f32_e32 v78, v78
	v_rndne_f32_e32 v79, v79
	v_rndne_f32_e32 v76, v76
	v_rndne_f32_e32 v77, v77
	v_cvt_pk_u8_f32 v74, v84, 0, 0
	v_cvt_pk_u8_f32 v74, v85, 1, v74
	v_cvt_pk_u8_f32 v75, v78, 0, 0
	v_cvt_pk_u8_f32 v75, v79, 1, v75
	v_cvt_pk_u8_f32 v74, v80, 2, v74
	v_cvt_pk_u8_f32 v74, v81, 3, v74
	v_cvt_pk_u8_f32 v75, v76, 2, v75
	v_cvt_pk_u8_f32 v75, v77, 3, v75
	v_mov_b64_e32 v[88:89], s[30:31]
	v_mad_i64_i32 v[88:89], s[0:1], v86, s55, v[88:89]
	v_lshl_add_u64 v[88:89], v[88:89], 0, v[140:141]
	s_mov_b64 s[0:1], 0
	v_mov_b32_e32 v246, v74
	v_mov_b32_e32 v247, v75

.LBB0_733:
	v_ffbh_u32_e32 v66, v151
	v_min_u32_e32 v68, 32, v66
	v_lshlrev_b64 v[66:67], v68, v[150:151]
	v_min_u32_e32 v66, 1, v66
	v_or_b32_e32 v66, v67, v66
	v_cvt_f32_u32_e32 v66, v66
	v_sub_u32_e32 v67, 32, v68
	v_add_u32_e32 v70, 0x80, v142
	s_mov_b64 s[0:1], -1
	v_ldexp_f32 v66, v66, v67
	v_fmamk_f32 v66, v66, 0x2e800000, v210
	s_nop 1
	v_rsq_f32_e32 v66, v66
	s_nop 0
	s_nop 0
	v_pk_mul_f32 v[64:65], v[64:65], v[66:67] op_sel_hi:[1,0]
	v_pk_mul_f32 v[68:69], v[62:63], v[66:67] op_sel_hi:[1,0]
	v_pk_mul_f32 v[60:61], v[60:61], v[66:67] op_sel_hi:[1,0]
	v_pk_mul_f32 v[62:63], v[58:59], v[66:67] op_sel_hi:[1,0]
	s_and_b64 vcc, exec, s[42:43]
	s_cbranch_vccnz .LBB0_735
	s_mov_b32 s98, 0xbfb8aa3b
	s_mov_b32 s32, 0x437f0000
	v_pk_mul_f32 v[68:69], v[68:69], s[98:99] op_sel_hi:[1,0]
	v_pk_mul_f32 v[64:65], v[64:65], s[98:99] op_sel_hi:[1,0]
	v_pk_mul_f32 v[62:63], v[62:63], s[98:99] op_sel_hi:[1,0]
	v_pk_mul_f32 v[60:61], v[60:61], s[98:99] op_sel_hi:[1,0]
	v_exp_f32_e32 v68, v68
	v_exp_f32_e32 v69, v69
	v_exp_f32_e32 v64, v64
	v_exp_f32_e32 v65, v65
	v_exp_f32_e32 v62, v62
	v_exp_f32_e32 v63, v63
	v_exp_f32_e32 v60, v60
	v_exp_f32_e32 v61, v61
	v_pk_add_f32 v[68:69], v[68:69], 1.0 op_sel_hi:[1,0]
	v_pk_add_f32 v[64:65], v[64:65], 1.0 op_sel_hi:[1,0]
	v_pk_add_f32 v[62:63], v[62:63], 1.0 op_sel_hi:[1,0]
	v_pk_add_f32 v[60:61], v[60:61], 1.0 op_sel_hi:[1,0]
	v_rcp_f32_e32 v68, v68
	v_rcp_f32_e32 v69, v69
	v_rcp_f32_e32 v64, v64
	v_rcp_f32_e32 v65, v65
	v_rcp_f32_e32 v62, v62
	v_rcp_f32_e32 v63, v63
	v_rcp_f32_e32 v60, v60
	v_rcp_f32_e32 v61, v61
	v_pk_mul_f32 v[68:69], v[68:69], s[32:33] op_sel_hi:[1,0]
	v_pk_mul_f32 v[64:65], v[64:65], s[32:33] op_sel_hi:[1,0]
	v_pk_mul_f32 v[62:63], v[62:63], s[32:33] op_sel_hi:[1,0]
	v_pk_mul_f32 v[60:61], v[60:61], s[32:33] op_sel_hi:[1,0]
	v_max_f32_e32 v68, 1.0, v68
	v_max_f32_e32 v69, 1.0, v69
	v_max_f32_e32 v64, 1.0, v64
	v_max_f32_e32 v65, 1.0, v65
	v_max_f32_e32 v62, 1.0, v62
	v_max_f32_e32 v63, 1.0, v63
	v_max_f32_e32 v60, 1.0, v60
	v_max_f32_e32 v61, 1.0, v61
	v_rndne_f32_e32 v68, v68
	v_rndne_f32_e32 v69, v69
	v_rndne_f32_e32 v64, v64
	v_rndne_f32_e32 v65, v65
	v_rndne_f32_e32 v62, v62
	v_rndne_f32_e32 v63, v63
	v_rndne_f32_e32 v60, v60
	v_rndne_f32_e32 v61, v61
	v_cvt_pk_u8_f32 v58, v68, 0, 0
	v_cvt_pk_u8_f32 v58, v69, 1, v58
	v_cvt_pk_u8_f32 v59, v62, 0, 0
	v_cvt_pk_u8_f32 v59, v63, 1, v59
	v_cvt_pk_u8_f32 v58, v64, 2, v58
	v_cvt_pk_u8_f32 v58, v65, 3, v58
	v_cvt_pk_u8_f32 v59, v60, 2, v59
	v_cvt_pk_u8_f32 v59, v61, 3, v59
	v_mov_b64_e32 v[72:73], s[30:31]
	v_mad_i64_i32 v[72:73], s[0:1], v70, s55, v[72:73]
	v_lshl_add_u64 v[72:73], v[72:73], 0, v[140:141]
	s_mov_b64 s[0:1], 0
	v_mov_b32_e32 v246, v58
	v_mov_b32_e32 v247, v59

.LBB0_741:
	v_ffbh_u32_e32 v50, v149
	v_min_u32_e32 v52, 32, v50
	v_lshlrev_b64 v[50:51], v52, v[148:149]
	v_min_u32_e32 v50, 1, v50
	v_or_b32_e32 v50, v51, v50
	v_cvt_f32_u32_e32 v50, v50
	v_sub_u32_e32 v51, 32, v52
	v_add_u32_e32 v54, 0x90, v142
	s_mov_b64 s[0:1], -1
	v_ldexp_f32 v50, v50, v51
	v_fmamk_f32 v50, v50, 0x2e800000, v210
	s_nop 1
	v_rsq_f32_e32 v50, v50
	s_nop 0
	s_nop 0
	v_pk_mul_f32 v[48:49], v[48:49], v[50:51] op_sel_hi:[1,0]
	v_pk_mul_f32 v[52:53], v[46:47], v[50:51] op_sel_hi:[1,0]
	v_pk_mul_f32 v[44:45], v[44:45], v[50:51] op_sel_hi:[1,0]
	v_pk_mul_f32 v[46:47], v[42:43], v[50:51] op_sel_hi:[1,0]
	s_and_b64 vcc, exec, s[42:43]
	s_cbranch_vccnz .LBB0_743
	s_mov_b32 s98, 0xbfb8aa3b
	s_mov_b32 s32, 0x437f0000
	v_pk_mul_f32 v[52:53], v[52:53], s[98:99] op_sel_hi:[1,0]
	v_pk_mul_f32 v[48:49], v[48:49], s[98:99] op_sel_hi:[1,0]
	v_pk_mul_f32 v[46:47], v[46:47], s[98:99] op_sel_hi:[1,0]
	v_pk_mul_f32 v[44:45], v[44:45], s[98:99] op_sel_hi:[1,0]
	v_exp_f32_e32 v52, v52
	v_exp_f32_e32 v53, v53
	v_exp_f32_e32 v48, v48
	v_exp_f32_e32 v49, v49
	v_exp_f32_e32 v46, v46
	v_exp_f32_e32 v47, v47
	v_exp_f32_e32 v44, v44
	v_exp_f32_e32 v45, v45
	v_pk_add_f32 v[52:53], v[52:53], 1.0 op_sel_hi:[1,0]
	v_pk_add_f32 v[48:49], v[48:49], 1.0 op_sel_hi:[1,0]
	v_pk_add_f32 v[46:47], v[46:47], 1.0 op_sel_hi:[1,0]
	v_pk_add_f32 v[44:45], v[44:45], 1.0 op_sel_hi:[1,0]
	v_rcp_f32_e32 v52, v52
	v_rcp_f32_e32 v53, v53
	v_rcp_f32_e32 v48, v48
	v_rcp_f32_e32 v49, v49
	v_rcp_f32_e32 v46, v46
	v_rcp_f32_e32 v47, v47
	v_rcp_f32_e32 v44, v44
	v_rcp_f32_e32 v45, v45
	v_pk_mul_f32 v[52:53], v[52:53], s[32:33] op_sel_hi:[1,0]
	v_pk_mul_f32 v[48:49], v[48:49], s[32:33] op_sel_hi:[1,0]
	v_pk_mul_f32 v[46:47], v[46:47], s[32:33] op_sel_hi:[1,0]
	v_pk_mul_f32 v[44:45], v[44:45], s[32:33] op_sel_hi:[1,0]
	v_max_f32_e32 v52, 1.0, v52
	v_max_f32_e32 v53, 1.0, v53
	v_max_f32_e32 v48, 1.0, v48
	v_max_f32_e32 v49, 1.0, v49
	v_max_f32_e32 v46, 1.0, v46
	v_max_f32_e32 v47, 1.0, v47
	v_max_f32_e32 v44, 1.0, v44
	v_max_f32_e32 v45, 1.0, v45
	v_rndne_f32_e32 v52, v52
	v_rndne_f32_e32 v53, v53
	v_rndne_f32_e32 v48, v48
	v_rndne_f32_e32 v49, v49
	v_rndne_f32_e32 v46, v46
	v_rndne_f32_e32 v47, v47
	v_rndne_f32_e32 v44, v44
	v_rndne_f32_e32 v45, v45
	v_cvt_pk_u8_f32 v42, v52, 0, 0
	v_cvt_pk_u8_f32 v42, v53, 1, v42
	v_cvt_pk_u8_f32 v43, v46, 0, 0
	v_cvt_pk_u8_f32 v43, v47, 1, v43
	v_cvt_pk_u8_f32 v42, v48, 2, v42
	v_cvt_pk_u8_f32 v42, v49, 3, v42
	v_cvt_pk_u8_f32 v43, v44, 2, v43
	v_cvt_pk_u8_f32 v43, v45, 3, v43
	v_mov_b64_e32 v[56:57], s[30:31]
	v_mad_i64_i32 v[56:57], s[0:1], v54, s55, v[56:57]
	v_lshl_add_u64 v[56:57], v[56:57], 0, v[140:141]
	s_mov_b64 s[0:1], 0
	v_mov_b32_e32 v246, v42
	v_mov_b32_e32 v247, v43

.LBB0_749:
	v_ffbh_u32_e32 v34, v147
	v_min_u32_e32 v36, 32, v34
	v_lshlrev_b64 v[34:35], v36, v[146:147]
	v_min_u32_e32 v34, 1, v34
	v_or_b32_e32 v34, v35, v34
	v_cvt_f32_u32_e32 v34, v34
	v_sub_u32_e32 v35, 32, v36
	v_add_u32_e32 v38, 0xa0, v142
	s_mov_b64 s[0:1], -1
	v_ldexp_f32 v34, v34, v35
	v_fmamk_f32 v34, v34, 0x2e800000, v210
	s_nop 1
	v_rsq_f32_e32 v34, v34
	s_nop 0
	s_nop 0
	v_pk_mul_f32 v[32:33], v[32:33], v[34:35] op_sel_hi:[1,0]
	v_pk_mul_f32 v[36:37], v[30:31], v[34:35] op_sel_hi:[1,0]
	v_pk_mul_f32 v[28:29], v[28:29], v[34:35] op_sel_hi:[1,0]
	v_pk_mul_f32 v[30:31], v[26:27], v[34:35] op_sel_hi:[1,0]
	s_and_b64 vcc, exec, s[42:43]
	s_cbranch_vccnz .LBB0_751
	s_mov_b32 s98, 0xbfb8aa3b
	s_mov_b32 s32, 0x437f0000
	v_pk_mul_f32 v[36:37], v[36:37], s[98:99] op_sel_hi:[1,0]
	v_pk_mul_f32 v[32:33], v[32:33], s[98:99] op_sel_hi:[1,0]
	v_pk_mul_f32 v[30:31], v[30:31], s[98:99] op_sel_hi:[1,0]
	v_pk_mul_f32 v[28:29], v[28:29], s[98:99] op_sel_hi:[1,0]
	v_exp_f32_e32 v36, v36
	v_exp_f32_e32 v37, v37
	v_exp_f32_e32 v32, v32
	v_exp_f32_e32 v33, v33
	v_exp_f32_e32 v30, v30
	v_exp_f32_e32 v31, v31
	v_exp_f32_e32 v28, v28
	v_exp_f32_e32 v29, v29
	v_pk_add_f32 v[36:37], v[36:37], 1.0 op_sel_hi:[1,0]
	v_pk_add_f32 v[32:33], v[32:33], 1.0 op_sel_hi:[1,0]
	v_pk_add_f32 v[30:31], v[30:31], 1.0 op_sel_hi:[1,0]
	v_pk_add_f32 v[28:29], v[28:29], 1.0 op_sel_hi:[1,0]
	v_rcp_f32_e32 v36, v36
	v_rcp_f32_e32 v37, v37
	v_rcp_f32_e32 v32, v32
	v_rcp_f32_e32 v33, v33
	v_rcp_f32_e32 v30, v30
	v_rcp_f32_e32 v31, v31
	v_rcp_f32_e32 v28, v28
	v_rcp_f32_e32 v29, v29
	v_pk_mul_f32 v[36:37], v[36:37], s[32:33] op_sel_hi:[1,0]
	v_pk_mul_f32 v[32:33], v[32:33], s[32:33] op_sel_hi:[1,0]
	v_pk_mul_f32 v[30:31], v[30:31], s[32:33] op_sel_hi:[1,0]
	v_pk_mul_f32 v[28:29], v[28:29], s[32:33] op_sel_hi:[1,0]
	v_max_f32_e32 v36, 1.0, v36
	v_max_f32_e32 v37, 1.0, v37
	v_max_f32_e32 v32, 1.0, v32
	v_max_f32_e32 v33, 1.0, v33
	v_max_f32_e32 v30, 1.0, v30
	v_max_f32_e32 v31, 1.0, v31
	v_max_f32_e32 v28, 1.0, v28
	v_max_f32_e32 v29, 1.0, v29
	v_rndne_f32_e32 v36, v36
	v_rndne_f32_e32 v37, v37
	v_rndne_f32_e32 v32, v32
	v_rndne_f32_e32 v33, v33
	v_rndne_f32_e32 v30, v30
	v_rndne_f32_e32 v31, v31
	v_rndne_f32_e32 v28, v28
	v_rndne_f32_e32 v29, v29
	v_cvt_pk_u8_f32 v26, v36, 0, 0
	v_cvt_pk_u8_f32 v26, v37, 1, v26
	v_cvt_pk_u8_f32 v27, v30, 0, 0
	v_cvt_pk_u8_f32 v27, v31, 1, v27
	v_cvt_pk_u8_f32 v26, v32, 2, v26
	v_cvt_pk_u8_f32 v26, v33, 3, v26
	v_cvt_pk_u8_f32 v27, v28, 2, v27
	v_cvt_pk_u8_f32 v27, v29, 3, v27
	v_mov_b64_e32 v[40:41], s[30:31]
	v_mad_i64_i32 v[40:41], s[0:1], v38, s55, v[40:41]
	v_lshl_add_u64 v[40:41], v[40:41], 0, v[140:141]
	s_mov_b64 s[0:1], 0
	v_mov_b32_e32 v246, v26
	v_mov_b32_e32 v247, v27

.LBB0_757:
	v_ffbh_u32_e32 v18, v145
	v_min_u32_e32 v20, 32, v18
	v_lshlrev_b64 v[18:19], v20, v[144:145]
	v_min_u32_e32 v18, 1, v18
	v_or_b32_e32 v18, v19, v18
	v_cvt_f32_u32_e32 v18, v18
	v_sub_u32_e32 v19, 32, v20
	v_add_u32_e32 v22, 0xb0, v142
	s_mov_b64 s[0:1], -1
	v_ldexp_f32 v18, v18, v19
	v_fmamk_f32 v18, v18, 0x2e800000, v210
	s_nop 1
	v_rsq_f32_e32 v18, v18
	s_nop 0
	s_nop 0
	v_pk_mul_f32 v[16:17], v[16:17], v[18:19] op_sel_hi:[1,0]
	v_pk_mul_f32 v[20:21], v[14:15], v[18:19] op_sel_hi:[1,0]
	v_pk_mul_f32 v[12:13], v[12:13], v[18:19] op_sel_hi:[1,0]
	v_pk_mul_f32 v[14:15], v[10:11], v[18:19] op_sel_hi:[1,0]
	s_and_b64 vcc, exec, s[42:43]
	s_cbranch_vccnz .LBB0_759
	s_mov_b32 s98, 0xbfb8aa3b
	s_mov_b32 s32, 0x437f0000
	v_pk_mul_f32 v[20:21], v[20:21], s[98:99] op_sel_hi:[1,0]
	v_pk_mul_f32 v[16:17], v[16:17], s[98:99] op_sel_hi:[1,0]
	v_pk_mul_f32 v[14:15], v[14:15], s[98:99] op_sel_hi:[1,0]
	v_pk_mul_f32 v[12:13], v[12:13], s[98:99] op_sel_hi:[1,0]
	v_exp_f32_e32 v20, v20
	v_exp_f32_e32 v21, v21
	v_exp_f32_e32 v16, v16
	v_exp_f32_e32 v17, v17
	v_exp_f32_e32 v14, v14
	v_exp_f32_e32 v15, v15
	v_exp_f32_e32 v12, v12
	v_exp_f32_e32 v13, v13
	v_pk_add_f32 v[20:21], v[20:21], 1.0 op_sel_hi:[1,0]
	v_pk_add_f32 v[16:17], v[16:17], 1.0 op_sel_hi:[1,0]
	v_pk_add_f32 v[14:15], v[14:15], 1.0 op_sel_hi:[1,0]
	v_pk_add_f32 v[12:13], v[12:13], 1.0 op_sel_hi:[1,0]
	v_rcp_f32_e32 v20, v20
	v_rcp_f32_e32 v21, v21
	v_rcp_f32_e32 v16, v16
	v_rcp_f32_e32 v17, v17
	v_rcp_f32_e32 v14, v14
	v_rcp_f32_e32 v15, v15
	v_rcp_f32_e32 v12, v12
	v_rcp_f32_e32 v13, v13
	v_pk_mul_f32 v[20:21], v[20:21], s[32:33] op_sel_hi:[1,0]
	v_pk_mul_f32 v[16:17], v[16:17], s[32:33] op_sel_hi:[1,0]
	v_pk_mul_f32 v[14:15], v[14:15], s[32:33] op_sel_hi:[1,0]
	v_pk_mul_f32 v[12:13], v[12:13], s[32:33] op_sel_hi:[1,0]
	v_max_f32_e32 v20, 1.0, v20
	v_max_f32_e32 v21, 1.0, v21
	v_max_f32_e32 v16, 1.0, v16
	v_max_f32_e32 v17, 1.0, v17
	v_max_f32_e32 v14, 1.0, v14
	v_max_f32_e32 v15, 1.0, v15
	v_max_f32_e32 v12, 1.0, v12
	v_max_f32_e32 v13, 1.0, v13
	v_rndne_f32_e32 v20, v20
	v_rndne_f32_e32 v21, v21
	v_rndne_f32_e32 v16, v16
	v_rndne_f32_e32 v17, v17
	v_rndne_f32_e32 v14, v14
	v_rndne_f32_e32 v15, v15
	v_rndne_f32_e32 v12, v12
	v_rndne_f32_e32 v13, v13
	v_cvt_pk_u8_f32 v10, v20, 0, 0
	v_cvt_pk_u8_f32 v10, v21, 1, v10
	v_cvt_pk_u8_f32 v11, v14, 0, 0
	v_cvt_pk_u8_f32 v11, v15, 1, v11
	v_cvt_pk_u8_f32 v10, v16, 2, v10
	v_cvt_pk_u8_f32 v10, v17, 3, v10
	v_cvt_pk_u8_f32 v11, v12, 2, v11
	v_cvt_pk_u8_f32 v11, v13, 3, v11
	v_mov_b64_e32 v[24:25], s[30:31]
	v_mad_i64_i32 v[24:25], s[0:1], v22, s55, v[24:25]
	v_lshl_add_u64 v[24:25], v[24:25], 0, v[140:141]
	s_mov_b64 s[0:1], 0
	v_mov_b32_e32 v246, v10
	v_mov_b32_e32 v247, v11
